# v4: state_scan inner loop rewritten with prefetched batches + GEMM epilogue ss loads hoisted + M1/M3 loads de-serialized (previous measure v13 was a diagnostic with the final norm run twice)
# speedup vs baseline: 1.0675x; 1.0207x over previous
; DI unsigned cvt_pk(float lo, float hi) { unsigned r; asm("v_cvt_pk_bf16_f32 %0, %1, %2" : "=v"(r) : "v"(lo), "v"(hi)); return r; }
; DI float siluf_(float x) { return x * sigmoidf_(x); }
;     __device__ __forceinline__ void operator()(const f32x4 (&acc)[2][2][4][2], const Unit& u, int wr, int wc, int fr, int fq) const {
;         const int row0 = u.pm * BM + wr * 64 + fr, col0 = u.pn * 128 + wc * 32 + 8 * fq;
; #pragma unroll
;         for (int ai = 0; ai < 2; ++ai)
; #pragma unroll
;             for (int m = 0; m < 4; ++m) {
;                 const int row = row0 + ai * HALF + m * 16;
;                 const float rs = rsqrtf(ss[row] * (1.f / DM) + EPS);
;                 float h[8];
; #pragma unroll
;                 for (int n = 0; n < 2; ++n)
; #pragma unroll
;                     for (int j = 0; j < 4; ++j) { const float gg = acc[ai][0][m][n][j] * rs, uu = acc[ai][1][m][n][j] * rs; h[4 * n + j] = siluf_(gg) * uu; }
;                 u32x4 w; w.x = cvt_pk(h[0], h[1]); w.y = cvt_pk(h[2], h[3]); w.z = cvt_pk(h[4], h[5]); w.w = cvt_pk(h[6], h[7]);
;                 *(u32x4*)(H + (size_t)row * DFF + col0) = w;
;             }
.LBB0_297:
	v_lshl_add_u32 v138, s41, 8, v155
	v_ashrrev_i32_e32 v139, 31, v138
	v_lshl_add_u64 v[140:141], v[138:139], 2, s[10:11]
	global_load_dword v139, v[140:141], off
	global_load_dword v162, v[140:141], off offset:64
	global_load_dword v163, v[140:141], off offset:128
	global_load_dword v164, v[140:141], off offset:192
	global_load_dword v165, v[140:141], off offset:512
	global_load_dword v166, v[140:141], off offset:576
	global_load_dword v167, v[140:141], off offset:640
	global_load_dword v168, v[140:141], off offset:704
	s_mov_b32 s15, 0x800000
	v_mov_b32_e32 v160, v120
	v_mov_b32_e32 v161, v124
	v_mov_b32_e32 v124, v121
	v_lshl_or_b32 v142, s40, 7, v157
	v_ashrrev_i32_e32 v143, 31, v142
	s_waitcnt vmcnt(0)
	v_fmamk_f32 v139, v139, 0x3a800000, v217
	v_cmp_gt_f32_e32 vcc, s15, v139
	v_mul_f32_e32 v154, 0x4b800000, v139
	s_nop 0
	v_cndmask_b32_e32 v139, v139, v154, vcc
	v_rsq_f32_e32 v139, v139
	s_nop 0
	v_mul_f32_e32 v154, 0x45800000, v139
	v_cndmask_b32_e32 v154, v139, v154, vcc
	v_pk_mul_f32 v[160:161], v[160:161], v[154:155] op_sel_hi:[1,0]
	s_nop 0
	v_mul_f32_e32 v120, 0xbfb8aa3b, v161
	v_exp_f32_e32 v120, v120
	s_nop 0
	v_add_f32_e32 v120, 1.0, v120
	v_rcp_f32_e32 v120, v120
	s_nop 0
	v_mul_f32_e32 v120, v161, v120
	v_mul_f32_e32 v139, v160, v120
	v_pk_mul_f32 v[120:121], v[124:125], v[154:155] op_sel_hi:[1,0]
	s_nop 0
	v_mul_f32_e32 v124, 0xbfb8aa3b, v121
	v_exp_f32_e32 v124, v124
	s_nop 0
	v_add_f32_e32 v124, 1.0, v124
	v_rcp_f32_e32 v124, v124
	s_nop 0
	v_mul_f32_e32 v121, v121, v124
	v_mul_f32_e32 v124, v120, v121
	v_mov_b32_e32 v120, v122
	v_mov_b32_e32 v121, v126
	v_pk_mul_f32 v[120:121], v[120:121], v[154:155] op_sel_hi:[1,0]
	v_mov_b32_e32 v126, v123
	v_mul_f32_e32 v122, 0xbfb8aa3b, v121
	v_exp_f32_e32 v122, v122
	s_nop 0
	v_add_f32_e32 v122, 1.0, v122
	v_rcp_f32_e32 v122, v122
	s_nop 0
	v_mul_f32_e32 v121, v121, v122
	v_mul_f32_e32 v122, v120, v121
	v_pk_mul_f32 v[120:121], v[126:127], v[154:155] op_sel_hi:[1,0]
	s_nop 0
	v_mul_f32_e32 v123, 0xbfb8aa3b, v121
	v_exp_f32_e32 v123, v123
	s_nop 0
	v_add_f32_e32 v123, 1.0, v123
	v_rcp_f32_e32 v123, v123
	s_nop 0
	v_mul_f32_e32 v121, v121, v123
	v_mul_f32_e32 v123, v120, v121
	v_mov_b32_e32 v120, v112
	v_mov_b32_e32 v121, v116
	v_pk_mul_f32 v[120:121], v[120:121], v[154:155] op_sel_hi:[1,0]
	v_mov_b32_e32 v116, v113
	v_mul_f32_e32 v112, 0xbfb8aa3b, v121
	v_exp_f32_e32 v112, v112
	s_nop 0
	v_add_f32_e32 v112, 1.0, v112
	v_rcp_f32_e32 v112, v112
	s_nop 0
	v_mul_f32_e32 v112, v121, v112
	v_mul_f32_e32 v120, v120, v112
	v_pk_mul_f32 v[112:113], v[116:117], v[154:155] op_sel_hi:[1,0]
	s_nop 0
	v_mul_f32_e32 v116, 0xbfb8aa3b, v113
	v_exp_f32_e32 v116, v116
	s_nop 0
	v_add_f32_e32 v116, 1.0, v116
	v_rcp_f32_e32 v116, v116
	s_nop 0
	v_mul_f32_e32 v113, v113, v116
	v_mul_f32_e32 v116, v112, v113
	v_mov_b32_e32 v112, v114
	v_mov_b32_e32 v113, v118
	v_pk_mul_f32 v[112:113], v[112:113], v[154:155] op_sel_hi:[1,0]
	v_mov_b32_e32 v118, v115
	v_mul_f32_e32 v114, 0xbfb8aa3b, v113
	v_exp_f32_e32 v114, v114
	s_nop 0
	v_add_f32_e32 v114, 1.0, v114
	v_rcp_f32_e32 v114, v114
	s_nop 0
	v_mul_f32_e32 v113, v113, v114
	v_mul_f32_e32 v117, v112, v113
	v_pk_mul_f32 v[112:113], v[118:119], v[154:155] op_sel_hi:[1,0]
	v_lshlrev_b64 v[118:119], 1, v[142:143]
	v_mul_f32_e32 v114, 0xbfb8aa3b, v113
	v_exp_f32_e32 v114, v114
	s_nop 0
	v_add_f32_e32 v114, 1.0, v114
	v_rcp_f32_e32 v114, v114
	s_nop 0
	v_mul_f32_e32 v113, v113, v114
	v_mul_f32_e32 v115, v112, v113
	v_cvt_pk_bf16_f32 v114, v120, v116
	v_cvt_pk_bf16_f32 v115, v117, v115
	v_mov_b64_e32 v[116:117], s[8:9]
	v_mad_i64_i32 v[120:121], s[2:3], v138, s64, v[116:117]
	v_lshl_add_u64 v[120:121], v[120:121], 0, v[118:119]
	v_cvt_pk_bf16_f32 v112, v139, v124
	v_cvt_pk_bf16_f32 v113, v122, v123
	global_store_dwordx4 v[120:121], v[112:115], off
	s_nop 0
	s_nop 0
	v_or_b32_e32 v113, 16, v138
	v_mov_b32_e32 v115, v108
	v_mov_b32_e32 v108, v105
	v_mov_b32_e32 v112, v162
	v_fmamk_f32 v112, v112, 0x3a800000, v217
	v_cmp_gt_f32_e32 vcc, s15, v112
	v_mul_f32_e32 v114, 0x4b800000, v112
	s_nop 0
	v_cndmask_b32_e32 v112, v112, v114, vcc
	v_rsq_f32_e32 v112, v112
	s_nop 0
	v_mul_f32_e32 v114, 0x45800000, v112
	v_cndmask_b32_e32 v112, v112, v114, vcc
	v_mov_b32_e32 v114, v104
	v_pk_mul_f32 v[114:115], v[114:115], v[112:113] op_sel_hi:[1,0]
	s_nop 0
	v_mul_f32_e32 v104, 0xbfb8aa3b, v115
	v_exp_f32_e32 v104, v104
	s_nop 0
	v_add_f32_e32 v104, 1.0, v104
	v_rcp_f32_e32 v104, v104
	s_nop 0
	v_mul_f32_e32 v104, v115, v104
	v_mul_f32_e32 v114, v114, v104
	v_pk_mul_f32 v[104:105], v[108:109], v[112:113] op_sel_hi:[1,0]
	s_nop 0
	v_mul_f32_e32 v108, 0xbfb8aa3b, v105
	v_exp_f32_e32 v108, v108
	s_nop 0
	v_add_f32_e32 v108, 1.0, v108
	v_rcp_f32_e32 v108, v108
	s_nop 0
	v_mul_f32_e32 v105, v105, v108
	v_mul_f32_e32 v108, v104, v105
	v_mov_b32_e32 v104, v106
	v_mov_b32_e32 v105, v110
	v_pk_mul_f32 v[104:105], v[104:105], v[112:113] op_sel_hi:[1,0]
	v_mov_b32_e32 v110, v107
	v_mul_f32_e32 v106, 0xbfb8aa3b, v105
	v_exp_f32_e32 v106, v106
	s_nop 0
	v_add_f32_e32 v106, 1.0, v106
	v_rcp_f32_e32 v106, v106
	s_nop 0
	v_mul_f32_e32 v105, v105, v106
	v_mul_f32_e32 v106, v104, v105
	v_pk_mul_f32 v[104:105], v[110:111], v[112:113] op_sel_hi:[1,0]
	s_nop 0
	v_mul_f32_e32 v107, 0xbfb8aa3b, v105
	v_exp_f32_e32 v107, v107
	s_nop 0
	v_add_f32_e32 v107, 1.0, v107
	v_rcp_f32_e32 v107, v107
	s_nop 0
	v_mul_f32_e32 v105, v105, v107
	v_mul_f32_e32 v107, v104, v105
	v_mov_b32_e32 v104, v96
	v_mov_b32_e32 v105, v100
	v_pk_mul_f32 v[104:105], v[104:105], v[112:113] op_sel_hi:[1,0]
	v_mov_b32_e32 v100, v97
	v_mul_f32_e32 v96, 0xbfb8aa3b, v105
	v_exp_f32_e32 v96, v96
	s_nop 0
	v_add_f32_e32 v96, 1.0, v96
; DI unsigned cvt_pk(float lo, float hi) { unsigned r; asm("v_cvt_pk_bf16_f32 %0, %1, %2" : "=v"(r) : "v"(lo), "v"(hi)); return r; }
; DI float siluf_(float x) { return x * sigmoidf_(x); }
;     __device__ __forceinline__ void operator()(const f32x4 (&acc)[2][2][4][2], const Unit& u, int wr, int wc, int fr, int fq) const {
;         const int row0 = u.pm * BM + wr * 64 + fr, col0 = u.pn * 128 + wc * 32 + 8 * fq;
; #pragma unroll
;         for (int ai = 0; ai < 2; ++ai)
; #pragma unroll
;             for (int m = 0; m < 4; ++m) {
;                 const int row = row0 + ai * HALF + m * 16;
;                 const float rs = rsqrtf(ss[row] * (1.f / DM) + EPS);
;                 float h[8];
; #pragma unroll
;                 for (int n = 0; n < 2; ++n)
; #pragma unroll
;                     for (int j = 0; j < 4; ++j) { const float gg = acc[ai][0][m][n][j] * rs, uu = acc[ai][1][m][n][j] * rs; h[4 * n + j] = siluf_(gg) * uu; }
;                 u32x4 w; w.x = cvt_pk(h[0], h[1]); w.y = cvt_pk(h[2], h[3]); w.z = cvt_pk(h[4], h[5]); w.w = cvt_pk(h[6], h[7]);
;                 *(u32x4*)(H + (size_t)row * DFF + col0) = w;
;             }
	v_rcp_f32_e32 v96, v96
	s_nop 0
	v_mul_f32_e32 v96, v105, v96
	v_mul_f32_e32 v104, v104, v96
	v_pk_mul_f32 v[96:97], v[100:101], v[112:113] op_sel_hi:[1,0]
	s_nop 0
	v_mul_f32_e32 v100, 0xbfb8aa3b, v97
	v_exp_f32_e32 v100, v100
	s_nop 0
	v_add_f32_e32 v100, 1.0, v100
	v_rcp_f32_e32 v100, v100
	s_nop 0
	v_mul_f32_e32 v97, v97, v100
	v_mul_f32_e32 v100, v96, v97
	v_mov_b32_e32 v96, v98
	v_mov_b32_e32 v97, v102
	v_pk_mul_f32 v[96:97], v[96:97], v[112:113] op_sel_hi:[1,0]
	v_mov_b32_e32 v102, v99
	v_mul_f32_e32 v98, 0xbfb8aa3b, v97
	v_exp_f32_e32 v98, v98
	s_nop 0
	v_add_f32_e32 v98, 1.0, v98
	v_rcp_f32_e32 v98, v98
	s_nop 0
	v_mul_f32_e32 v97, v97, v98
	v_mul_f32_e32 v101, v96, v97
	v_pk_mul_f32 v[96:97], v[102:103], v[112:113] op_sel_hi:[1,0]
	s_nop 0
	v_mul_f32_e32 v98, 0xbfb8aa3b, v97
	v_exp_f32_e32 v98, v98
	s_nop 0
	v_add_f32_e32 v98, 1.0, v98
	v_rcp_f32_e32 v98, v98
	s_nop 0
	v_mul_f32_e32 v97, v97, v98
	v_mul_f32_e32 v99, v96, v97
	v_cvt_pk_bf16_f32 v98, v104, v100
	v_cvt_pk_bf16_f32 v99, v101, v99
	v_mad_i64_i32 v[100:101], s[2:3], v113, s64, v[116:117]
	v_lshl_add_u64 v[100:101], v[100:101], 0, v[118:119]
	v_cvt_pk_bf16_f32 v96, v114, v108
	v_cvt_pk_bf16_f32 v97, v106, v107
	global_store_dwordx4 v[100:101], v[96:99], off
	s_nop 0
	s_nop 0
	v_or_b32_e32 v97, 32, v138
	v_mov_b32_e32 v99, v92
	v_mov_b32_e32 v92, v89
	v_mov_b32_e32 v96, v163
	v_fmamk_f32 v96, v96, 0x3a800000, v217
	v_cmp_gt_f32_e32 vcc, s15, v96
	v_mul_f32_e32 v98, 0x4b800000, v96
	s_nop 0
	v_cndmask_b32_e32 v96, v96, v98, vcc
	v_rsq_f32_e32 v96, v96
	s_nop 0
	v_mul_f32_e32 v98, 0x45800000, v96
	v_cndmask_b32_e32 v96, v96, v98, vcc
	v_mov_b32_e32 v98, v88
	v_pk_mul_f32 v[98:99], v[98:99], v[96:97] op_sel_hi:[1,0]
	s_nop 0
	v_mul_f32_e32 v88, 0xbfb8aa3b, v99
	v_exp_f32_e32 v88, v88
	s_nop 0
	v_add_f32_e32 v88, 1.0, v88
	v_rcp_f32_e32 v88, v88
	s_nop 0
	v_mul_f32_e32 v88, v99, v88
	v_mul_f32_e32 v98, v98, v88
	v_pk_mul_f32 v[88:89], v[92:93], v[96:97] op_sel_hi:[1,0]
	s_nop 0
	v_mul_f32_e32 v92, 0xbfb8aa3b, v89
	v_exp_f32_e32 v92, v92
	s_nop 0
	v_add_f32_e32 v92, 1.0, v92
	v_rcp_f32_e32 v92, v92
	s_nop 0
	v_mul_f32_e32 v89, v89, v92
	v_mul_f32_e32 v92, v88, v89
	v_mov_b32_e32 v88, v90
	v_mov_b32_e32 v89, v94
	v_pk_mul_f32 v[88:89], v[88:89], v[96:97] op_sel_hi:[1,0]
	v_mov_b32_e32 v94, v91
	v_mul_f32_e32 v90, 0xbfb8aa3b, v89
	v_exp_f32_e32 v90, v90
	s_nop 0
	v_add_f32_e32 v90, 1.0, v90
	v_rcp_f32_e32 v90, v90
	s_nop 0
	v_mul_f32_e32 v89, v89, v90
	v_mul_f32_e32 v90, v88, v89
	v_pk_mul_f32 v[88:89], v[94:95], v[96:97] op_sel_hi:[1,0]
	s_nop 0
	v_mul_f32_e32 v91, 0xbfb8aa3b, v89
	v_exp_f32_e32 v91, v91
	s_nop 0
	v_add_f32_e32 v91, 1.0, v91
	v_rcp_f32_e32 v91, v91
	s_nop 0
	v_mul_f32_e32 v89, v89, v91
	v_mul_f32_e32 v91, v88, v89
	v_mov_b32_e32 v88, v80
	v_mov_b32_e32 v89, v84
	v_pk_mul_f32 v[88:89], v[88:89], v[96:97] op_sel_hi:[1,0]
	v_mov_b32_e32 v84, v81
	v_mul_f32_e32 v80, 0xbfb8aa3b, v89
	v_exp_f32_e32 v80, v80
	s_nop 0
	v_add_f32_e32 v80, 1.0, v80
	v_rcp_f32_e32 v80, v80
	s_nop 0
	v_mul_f32_e32 v80, v89, v80
	v_mul_f32_e32 v88, v88, v80
	v_pk_mul_f32 v[80:81], v[84:85], v[96:97] op_sel_hi:[1,0]
	s_nop 0
	v_mul_f32_e32 v84, 0xbfb8aa3b, v81
	v_exp_f32_e32 v84, v84
	s_nop 0
	v_add_f32_e32 v84, 1.0, v84
	v_rcp_f32_e32 v84, v84
	s_nop 0
	v_mul_f32_e32 v81, v81, v84
	v_mul_f32_e32 v84, v80, v81
	v_mov_b32_e32 v80, v82
	v_mov_b32_e32 v81, v86
	v_pk_mul_f32 v[80:81], v[80:81], v[96:97] op_sel_hi:[1,0]
	v_mov_b32_e32 v86, v83
	v_mul_f32_e32 v82, 0xbfb8aa3b, v81
	v_exp_f32_e32 v82, v82
	s_nop 0
	v_add_f32_e32 v82, 1.0, v82
	v_rcp_f32_e32 v82, v82
	s_nop 0
	v_mul_f32_e32 v81, v81, v82
	v_mul_f32_e32 v85, v80, v81
	v_pk_mul_f32 v[80:81], v[86:87], v[96:97] op_sel_hi:[1,0]
	s_nop 0
	v_mul_f32_e32 v82, 0xbfb8aa3b, v81
	v_exp_f32_e32 v82, v82
	s_nop 0
	v_add_f32_e32 v82, 1.0, v82
	v_rcp_f32_e32 v82, v82
	s_nop 0
	v_mul_f32_e32 v81, v81, v82
	v_mul_f32_e32 v83, v80, v81
	v_cvt_pk_bf16_f32 v82, v88, v84
	v_cvt_pk_bf16_f32 v83, v85, v83
	v_mad_i64_i32 v[84:85], s[2:3], v97, s64, v[116:117]
	v_lshl_add_u64 v[84:85], v[84:85], 0, v[118:119]
	v_cvt_pk_bf16_f32 v80, v98, v92
	v_cvt_pk_bf16_f32 v81, v90, v91
	global_store_dwordx4 v[84:85], v[80:83], off
	s_nop 0
	s_nop 0
	v_or_b32_e32 v81, 48, v138
	v_mov_b32_e32 v83, v76
	v_mov_b32_e32 v76, v73
	v_mov_b32_e32 v80, v164
	v_fmamk_f32 v80, v80, 0x3a800000, v217
	v_cmp_gt_f32_e32 vcc, s15, v80
	v_mul_f32_e32 v82, 0x4b800000, v80
	s_nop 0
	v_cndmask_b32_e32 v80, v80, v82, vcc
	v_rsq_f32_e32 v80, v80
	s_nop 0
	v_mul_f32_e32 v82, 0x45800000, v80
	v_cndmask_b32_e32 v80, v80, v82, vcc
	v_mov_b32_e32 v82, v72
	v_pk_mul_f32 v[82:83], v[82:83], v[80:81] op_sel_hi:[1,0]
	s_nop 0
	v_mul_f32_e32 v72, 0xbfb8aa3b, v83
	v_exp_f32_e32 v72, v72
	s_nop 0
	v_add_f32_e32 v72, 1.0, v72
	v_rcp_f32_e32 v72, v72
	s_nop 0
	v_mul_f32_e32 v72, v83, v72
	v_mul_f32_e32 v82, v82, v72
	v_pk_mul_f32 v[72:73], v[76:77], v[80:81] op_sel_hi:[1,0]
	s_nop 0
	v_mul_f32_e32 v76, 0xbfb8aa3b, v73
	v_exp_f32_e32 v76, v76
	s_nop 0
	v_add_f32_e32 v76, 1.0, v76
	v_rcp_f32_e32 v76, v76
	s_nop 0
	v_mul_f32_e32 v73, v73, v76
	v_mul_f32_e32 v76, v72, v73
	v_mov_b32_e32 v72, v74
	v_mov_b32_e32 v73, v78
	v_pk_mul_f32 v[72:73], v[72:73], v[80:81] op_sel_hi:[1,0]
	v_mov_b32_e32 v78, v75
	v_mul_f32_e32 v74, 0xbfb8aa3b, v73
	v_exp_f32_e32 v74, v74
	s_nop 0
	v_add_f32_e32 v74, 1.0, v74
	v_rcp_f32_e32 v74, v74
	s_nop 0
	v_mul_f32_e32 v73, v73, v74
	v_mul_f32_e32 v74, v72, v73
	v_pk_mul_f32 v[72:73], v[78:79], v[80:81] op_sel_hi:[1,0]
	s_nop 0
	v_mul_f32_e32 v75, 0xbfb8aa3b, v73
	v_exp_f32_e32 v75, v75
	s_nop 0
	v_add_f32_e32 v75, 1.0, v75
	v_rcp_f32_e32 v75, v75
	s_nop 0
	v_mul_f32_e32 v73, v73, v75
; DI unsigned cvt_pk(float lo, float hi) { unsigned r; asm("v_cvt_pk_bf16_f32 %0, %1, %2" : "=v"(r) : "v"(lo), "v"(hi)); return r; }
; DI float siluf_(float x) { return x * sigmoidf_(x); }
;     __device__ __forceinline__ void operator()(const f32x4 (&acc)[2][2][4][2], const Unit& u, int wr, int wc, int fr, int fq) const {
;         const int row0 = u.pm * BM + wr * 64 + fr, col0 = u.pn * 128 + wc * 32 + 8 * fq;
; #pragma unroll
;         for (int ai = 0; ai < 2; ++ai)
; #pragma unroll
;             for (int m = 0; m < 4; ++m) {
;                 const int row = row0 + ai * HALF + m * 16;
;                 const float rs = rsqrtf(ss[row] * (1.f / DM) + EPS);
;                 float h[8];
; #pragma unroll
;                 for (int n = 0; n < 2; ++n)
; #pragma unroll
;                     for (int j = 0; j < 4; ++j) { const float gg = acc[ai][0][m][n][j] * rs, uu = acc[ai][1][m][n][j] * rs; h[4 * n + j] = siluf_(gg) * uu; }
;                 u32x4 w; w.x = cvt_pk(h[0], h[1]); w.y = cvt_pk(h[2], h[3]); w.z = cvt_pk(h[4], h[5]); w.w = cvt_pk(h[6], h[7]);
;                 *(u32x4*)(H + (size_t)row * DFF + col0) = w;
;             }
	v_mul_f32_e32 v75, v72, v73
	v_mov_b32_e32 v72, v64
	v_mov_b32_e32 v73, v68
	v_pk_mul_f32 v[72:73], v[72:73], v[80:81] op_sel_hi:[1,0]
	v_mov_b32_e32 v68, v65
	v_mul_f32_e32 v64, 0xbfb8aa3b, v73
	v_exp_f32_e32 v64, v64
	s_nop 0
	v_add_f32_e32 v64, 1.0, v64
	v_rcp_f32_e32 v64, v64
	s_nop 0
	v_mul_f32_e32 v64, v73, v64
	v_mul_f32_e32 v72, v72, v64
	v_pk_mul_f32 v[64:65], v[68:69], v[80:81] op_sel_hi:[1,0]
	s_nop 0
	v_mul_f32_e32 v68, 0xbfb8aa3b, v65
	v_exp_f32_e32 v68, v68
	s_nop 0
	v_add_f32_e32 v68, 1.0, v68
	v_rcp_f32_e32 v68, v68
	s_nop 0
	v_mul_f32_e32 v65, v65, v68
	v_mul_f32_e32 v68, v64, v65
	v_mov_b32_e32 v64, v66
	v_mov_b32_e32 v65, v70
	v_pk_mul_f32 v[64:65], v[64:65], v[80:81] op_sel_hi:[1,0]
	v_mov_b32_e32 v70, v67
	v_mul_f32_e32 v66, 0xbfb8aa3b, v65
	v_exp_f32_e32 v66, v66
	s_nop 0
	v_add_f32_e32 v66, 1.0, v66
	v_rcp_f32_e32 v66, v66
	s_nop 0
	v_mul_f32_e32 v65, v65, v66
	v_mul_f32_e32 v69, v64, v65
	v_pk_mul_f32 v[64:65], v[70:71], v[80:81] op_sel_hi:[1,0]
	s_nop 0
	v_mul_f32_e32 v66, 0xbfb8aa3b, v65
	v_exp_f32_e32 v66, v66
	s_nop 0
	v_add_f32_e32 v66, 1.0, v66
	v_rcp_f32_e32 v66, v66
	s_nop 0
	v_mul_f32_e32 v65, v65, v66
	v_mul_f32_e32 v67, v64, v65
	v_cvt_pk_bf16_f32 v66, v72, v68
	v_cvt_pk_bf16_f32 v67, v69, v67
	v_mad_i64_i32 v[68:69], s[2:3], v81, s64, v[116:117]
	v_lshl_add_u64 v[68:69], v[68:69], 0, v[118:119]
	v_cvt_pk_bf16_f32 v64, v82, v76
	v_cvt_pk_bf16_f32 v65, v74, v75
	global_store_dwordx4 v[68:69], v[64:67], off
	s_nop 0
	s_nop 0
	v_add_u32_e32 v65, 0x80, v138
	v_mov_b32_e32 v67, v60
	v_mov_b32_e32 v60, v57
	v_mov_b32_e32 v64, v165
	v_fmamk_f32 v64, v64, 0x3a800000, v217
	v_cmp_gt_f32_e32 vcc, s15, v64
	v_mul_f32_e32 v66, 0x4b800000, v64
	s_nop 0
	v_cndmask_b32_e32 v64, v64, v66, vcc
	v_rsq_f32_e32 v64, v64
	s_nop 0
	v_mul_f32_e32 v66, 0x45800000, v64
	v_cndmask_b32_e32 v64, v64, v66, vcc
	v_mov_b32_e32 v66, v56
	v_pk_mul_f32 v[66:67], v[66:67], v[64:65] op_sel_hi:[1,0]
	s_nop 0
	v_mul_f32_e32 v56, 0xbfb8aa3b, v67
	v_exp_f32_e32 v56, v56
	s_nop 0
	v_add_f32_e32 v56, 1.0, v56
	v_rcp_f32_e32 v56, v56
	s_nop 0
	v_mul_f32_e32 v56, v67, v56
	v_mul_f32_e32 v66, v66, v56
	v_pk_mul_f32 v[56:57], v[60:61], v[64:65] op_sel_hi:[1,0]
	s_nop 0
	v_mul_f32_e32 v60, 0xbfb8aa3b, v57
	v_exp_f32_e32 v60, v60
	s_nop 0
	v_add_f32_e32 v60, 1.0, v60
	v_rcp_f32_e32 v60, v60
	s_nop 0
	v_mul_f32_e32 v57, v57, v60
	v_mul_f32_e32 v60, v56, v57
	v_mov_b32_e32 v56, v58
	v_mov_b32_e32 v57, v62
	v_pk_mul_f32 v[56:57], v[56:57], v[64:65] op_sel_hi:[1,0]
	v_mov_b32_e32 v62, v59
	v_mul_f32_e32 v58, 0xbfb8aa3b, v57
	v_exp_f32_e32 v58, v58
	s_nop 0
	v_add_f32_e32 v58, 1.0, v58
	v_rcp_f32_e32 v58, v58
	s_nop 0
	v_mul_f32_e32 v57, v57, v58
	v_mul_f32_e32 v58, v56, v57
	v_pk_mul_f32 v[56:57], v[62:63], v[64:65] op_sel_hi:[1,0]
	s_nop 0
	v_mul_f32_e32 v59, 0xbfb8aa3b, v57
	v_exp_f32_e32 v59, v59
	s_nop 0
	v_add_f32_e32 v59, 1.0, v59
	v_rcp_f32_e32 v59, v59
	s_nop 0
	v_mul_f32_e32 v57, v57, v59
	v_mul_f32_e32 v59, v56, v57
	v_mov_b32_e32 v56, v48
	v_mov_b32_e32 v57, v52
	v_pk_mul_f32 v[56:57], v[56:57], v[64:65] op_sel_hi:[1,0]
	v_mov_b32_e32 v52, v49
	v_mul_f32_e32 v48, 0xbfb8aa3b, v57
	v_exp_f32_e32 v48, v48
	s_nop 0
	v_add_f32_e32 v48, 1.0, v48
	v_rcp_f32_e32 v48, v48
	s_nop 0
	v_mul_f32_e32 v48, v57, v48
	v_mul_f32_e32 v56, v56, v48
	v_pk_mul_f32 v[48:49], v[52:53], v[64:65] op_sel_hi:[1,0]
	s_nop 0
	v_mul_f32_e32 v52, 0xbfb8aa3b, v49
	v_exp_f32_e32 v52, v52
	s_nop 0
	v_add_f32_e32 v52, 1.0, v52
	v_rcp_f32_e32 v52, v52
	s_nop 0
	v_mul_f32_e32 v49, v49, v52
	v_mul_f32_e32 v52, v48, v49
	v_mov_b32_e32 v48, v50
	v_mov_b32_e32 v49, v54
	v_pk_mul_f32 v[48:49], v[48:49], v[64:65] op_sel_hi:[1,0]
	v_mov_b32_e32 v54, v51
	v_mul_f32_e32 v50, 0xbfb8aa3b, v49
	v_exp_f32_e32 v50, v50
	s_nop 0
	v_add_f32_e32 v50, 1.0, v50
	v_rcp_f32_e32 v50, v50
	s_nop 0
	v_mul_f32_e32 v49, v49, v50
	v_mul_f32_e32 v53, v48, v49
	v_pk_mul_f32 v[48:49], v[54:55], v[64:65] op_sel_hi:[1,0]
	s_nop 0
	v_mul_f32_e32 v50, 0xbfb8aa3b, v49
	v_exp_f32_e32 v50, v50
	s_nop 0
	v_add_f32_e32 v50, 1.0, v50
	v_rcp_f32_e32 v50, v50
	s_nop 0
	v_mul_f32_e32 v49, v49, v50
	v_mul_f32_e32 v51, v48, v49
	v_cvt_pk_bf16_f32 v50, v56, v52
	v_cvt_pk_bf16_f32 v51, v53, v51
	v_mad_i64_i32 v[52:53], s[2:3], v65, s64, v[116:117]
	v_lshl_add_u64 v[52:53], v[52:53], 0, v[118:119]
	v_cvt_pk_bf16_f32 v48, v66, v60
	v_cvt_pk_bf16_f32 v49, v58, v59
	global_store_dwordx4 v[52:53], v[48:51], off
	s_nop 0
	s_nop 0
	v_add_u32_e32 v49, 0x90, v138
	v_mov_b32_e32 v51, v44
	v_mov_b32_e32 v44, v41
	v_mov_b32_e32 v48, v166
	v_fmamk_f32 v48, v48, 0x3a800000, v217
	v_cmp_gt_f32_e32 vcc, s15, v48
	v_mul_f32_e32 v50, 0x4b800000, v48
	s_nop 0
	v_cndmask_b32_e32 v48, v48, v50, vcc
	v_rsq_f32_e32 v48, v48
	s_nop 0
	v_mul_f32_e32 v50, 0x45800000, v48
	v_cndmask_b32_e32 v48, v48, v50, vcc
	v_mov_b32_e32 v50, v40
	v_pk_mul_f32 v[50:51], v[50:51], v[48:49] op_sel_hi:[1,0]
	s_nop 0
	v_mul_f32_e32 v40, 0xbfb8aa3b, v51
	v_exp_f32_e32 v40, v40
	s_nop 0
	v_add_f32_e32 v40, 1.0, v40
	v_rcp_f32_e32 v40, v40
	s_nop 0
	v_mul_f32_e32 v40, v51, v40
	v_mul_f32_e32 v50, v50, v40
	v_pk_mul_f32 v[40:41], v[44:45], v[48:49] op_sel_hi:[1,0]
	s_nop 0
	v_mul_f32_e32 v44, 0xbfb8aa3b, v41
	v_exp_f32_e32 v44, v44
	s_nop 0
	v_add_f32_e32 v44, 1.0, v44
	v_rcp_f32_e32 v44, v44
	s_nop 0
	v_mul_f32_e32 v41, v41, v44
	v_mul_f32_e32 v44, v40, v41
	v_mov_b32_e32 v40, v42
	v_mov_b32_e32 v41, v46
	v_pk_mul_f32 v[40:41], v[40:41], v[48:49] op_sel_hi:[1,0]
	v_mov_b32_e32 v46, v43
	v_mul_f32_e32 v42, 0xbfb8aa3b, v41
	v_exp_f32_e32 v42, v42
	s_nop 0
	v_add_f32_e32 v42, 1.0, v42
	v_rcp_f32_e32 v42, v42
	s_nop 0
	v_mul_f32_e32 v41, v41, v42
	v_mul_f32_e32 v42, v40, v41
; DI unsigned cvt_pk(float lo, float hi) { unsigned r; asm("v_cvt_pk_bf16_f32 %0, %1, %2" : "=v"(r) : "v"(lo), "v"(hi)); return r; }
; DI float siluf_(float x) { return x * sigmoidf_(x); }
;     __device__ __forceinline__ void operator()(const f32x4 (&acc)[2][2][4][2], const Unit& u, int wr, int wc, int fr, int fq) const {
;     ...
;                 const int row = row0 + ai * HALF + m * 16;
;                 const float rs = rsqrtf(ss[row] * (1.f / DM) + EPS);
;                 float h[8];
; #pragma unroll
;                 for (int n = 0; n < 2; ++n)
; #pragma unroll
;                     for (int j = 0; j < 4; ++j) { const float gg = acc[ai][0][m][n][j] * rs, uu = acc[ai][1][m][n][j] * rs; h[4 * n + j] = siluf_(gg) * uu; }
;                 u32x4 w; w.x = cvt_pk(h[0], h[1]); w.y = cvt_pk(h[2], h[3]); w.z = cvt_pk(h[4], h[5]); w.w = cvt_pk(h[6], h[7]);
;                 *(u32x4*)(H + (size_t)row * DFF + col0) = w;
	v_pk_mul_f32 v[40:41], v[46:47], v[48:49] op_sel_hi:[1,0]
	s_nop 0
	v_mul_f32_e32 v43, 0xbfb8aa3b, v41
	v_exp_f32_e32 v43, v43
	s_nop 0
	v_add_f32_e32 v43, 1.0, v43
	v_rcp_f32_e32 v43, v43
	s_nop 0
	v_mul_f32_e32 v41, v41, v43
	v_mul_f32_e32 v43, v40, v41
	v_mov_b32_e32 v40, v32
	v_mov_b32_e32 v41, v36
	v_pk_mul_f32 v[40:41], v[40:41], v[48:49] op_sel_hi:[1,0]
	v_mov_b32_e32 v36, v33
	v_mul_f32_e32 v32, 0xbfb8aa3b, v41
	v_exp_f32_e32 v32, v32
	s_nop 0
	v_add_f32_e32 v32, 1.0, v32
	v_rcp_f32_e32 v32, v32
	s_nop 0
	v_mul_f32_e32 v32, v41, v32
	v_mul_f32_e32 v40, v40, v32
	v_pk_mul_f32 v[32:33], v[36:37], v[48:49] op_sel_hi:[1,0]
	s_nop 0
	v_mul_f32_e32 v36, 0xbfb8aa3b, v33
	v_exp_f32_e32 v36, v36
	s_nop 0
	v_add_f32_e32 v36, 1.0, v36
	v_rcp_f32_e32 v36, v36
	s_nop 0
	v_mul_f32_e32 v33, v33, v36
	v_mul_f32_e32 v36, v32, v33
	v_mov_b32_e32 v32, v34
	v_mov_b32_e32 v33, v38
	v_pk_mul_f32 v[32:33], v[32:33], v[48:49] op_sel_hi:[1,0]
	v_mov_b32_e32 v38, v35
	v_mul_f32_e32 v34, 0xbfb8aa3b, v33
	v_exp_f32_e32 v34, v34
	s_nop 0
	v_add_f32_e32 v34, 1.0, v34
	v_rcp_f32_e32 v34, v34
	s_nop 0
	v_mul_f32_e32 v33, v33, v34
	v_mul_f32_e32 v37, v32, v33
	v_pk_mul_f32 v[32:33], v[38:39], v[48:49] op_sel_hi:[1,0]
	s_nop 0
	v_mul_f32_e32 v34, 0xbfb8aa3b, v33
	v_exp_f32_e32 v34, v34
	s_nop 0
	v_add_f32_e32 v34, 1.0, v34
	v_rcp_f32_e32 v34, v34
	s_nop 0
	v_mul_f32_e32 v33, v33, v34
	v_mul_f32_e32 v35, v32, v33
	v_cvt_pk_bf16_f32 v34, v40, v36
	v_cvt_pk_bf16_f32 v35, v37, v35
	v_mad_i64_i32 v[36:37], s[2:3], v49, s64, v[116:117]
	v_lshl_add_u64 v[36:37], v[36:37], 0, v[118:119]
	v_cvt_pk_bf16_f32 v32, v50, v44
	v_cvt_pk_bf16_f32 v33, v42, v43
	global_store_dwordx4 v[36:37], v[32:35], off
	s_nop 0
	s_nop 0
	v_add_u32_e32 v33, 0xa0, v138
	v_mov_b32_e32 v35, v28
	v_mov_b32_e32 v28, v25
	v_mov_b32_e32 v32, v167
	v_fmamk_f32 v32, v32, 0x3a800000, v217
	v_cmp_gt_f32_e32 vcc, s15, v32
	v_mul_f32_e32 v34, 0x4b800000, v32
	s_nop 0
	v_cndmask_b32_e32 v32, v32, v34, vcc
	v_rsq_f32_e32 v32, v32
	s_nop 0
	v_mul_f32_e32 v34, 0x45800000, v32
	v_cndmask_b32_e32 v32, v32, v34, vcc
	v_mov_b32_e32 v34, v24
	v_pk_mul_f32 v[34:35], v[34:35], v[32:33] op_sel_hi:[1,0]
	s_nop 0
	v_mul_f32_e32 v24, 0xbfb8aa3b, v35
	v_exp_f32_e32 v24, v24
	s_nop 0
	v_add_f32_e32 v24, 1.0, v24
	v_rcp_f32_e32 v24, v24
	s_nop 0
	v_mul_f32_e32 v24, v35, v24
	v_mul_f32_e32 v34, v34, v24
	v_pk_mul_f32 v[24:25], v[28:29], v[32:33] op_sel_hi:[1,0]
	s_nop 0
	v_mul_f32_e32 v28, 0xbfb8aa3b, v25
	v_exp_f32_e32 v28, v28
	s_nop 0
	v_add_f32_e32 v28, 1.0, v28
	v_rcp_f32_e32 v28, v28
	s_nop 0
	v_mul_f32_e32 v25, v25, v28
	v_mul_f32_e32 v28, v24, v25
	v_mov_b32_e32 v24, v26
	v_mov_b32_e32 v25, v30
	v_pk_mul_f32 v[24:25], v[24:25], v[32:33] op_sel_hi:[1,0]
	v_mov_b32_e32 v30, v27
	v_mul_f32_e32 v26, 0xbfb8aa3b, v25
	v_exp_f32_e32 v26, v26
	s_nop 0
	v_add_f32_e32 v26, 1.0, v26
	v_rcp_f32_e32 v26, v26
	s_nop 0
	v_mul_f32_e32 v25, v25, v26
	v_mul_f32_e32 v26, v24, v25
	v_pk_mul_f32 v[24:25], v[30:31], v[32:33] op_sel_hi:[1,0]
	s_nop 0
	v_mul_f32_e32 v27, 0xbfb8aa3b, v25
	v_exp_f32_e32 v27, v27
	s_nop 0
	v_add_f32_e32 v27, 1.0, v27
	v_rcp_f32_e32 v27, v27
	s_nop 0
	v_mul_f32_e32 v25, v25, v27
	v_mul_f32_e32 v27, v24, v25
	v_mov_b32_e32 v24, v16
	v_mov_b32_e32 v25, v20
	v_pk_mul_f32 v[24:25], v[24:25], v[32:33] op_sel_hi:[1,0]
	v_mov_b32_e32 v20, v17
	v_mul_f32_e32 v16, 0xbfb8aa3b, v25
	v_exp_f32_e32 v16, v16
	s_nop 0
	v_add_f32_e32 v16, 1.0, v16
	v_rcp_f32_e32 v16, v16
	s_nop 0
	v_mul_f32_e32 v16, v25, v16
	v_mul_f32_e32 v24, v24, v16
	v_pk_mul_f32 v[16:17], v[20:21], v[32:33] op_sel_hi:[1,0]
	s_nop 0
	v_mul_f32_e32 v20, 0xbfb8aa3b, v17
	v_exp_f32_e32 v20, v20
	s_nop 0
	v_add_f32_e32 v20, 1.0, v20
	v_rcp_f32_e32 v20, v20
	s_nop 0
	v_mul_f32_e32 v17, v17, v20
	v_mul_f32_e32 v20, v16, v17
	v_mov_b32_e32 v16, v18
; DI unsigned cvt_pk(float lo, float hi) { unsigned r; asm("v_cvt_pk_bf16_f32 %0, %1, %2" : "=v"(r) : "v"(lo), "v"(hi)); return r; }
; DI float siluf_(float x) { return x * sigmoidf_(x); }
; #define PG8_BAR __builtin_amdgcn_s_barrier()
; template <class Epi, class Sched, bool ALIGN_EPI = false, bool SP2 = false>
; __device__ __forceinline__ void gemm_phase(PG8_LAS unsigned char* lds, const Gemm g, const Sched& S, const Epi& E) {
;     ...
;         if constexpr (ALIGN_EPI) { if (wr == 0) PG8_BAR; }
;         E(acc, cur, wr, wc, fr, fq); S.done(cur);
;         if (!has_next) break;
; #pragma unroll
;         for (int a = 0; a < 2; ++a)
; #pragma unroll
;             for (int b = 0; b < 2; ++b)
; #pragma unroll
;                 for (int m = 0; m < 4; ++m)
; #pragma unroll
;                     for (int n = 0; n < 2; ++n) acc[a][b][m][n] = (f32x4){0.f, 0.f, 0.f, 0.f};
;         cur = nxt; cA = nA; cB = nB; ++ui;
;         if constexpr (ALIGN_EPI) { if (wr == 1) PG8_BAR; }
;     __device__ __forceinline__ void operator()(const f32x4 (&acc)[2][2][4][2], const Unit& u, int wr, int wc, int fr, int fq) const {
;     ...
;                 const int row = row0 + ai * HALF + m * 16;
;                 const float rs = rsqrtf(ss[row] * (1.f / DM) + EPS);
;                 float h[8];
; #pragma unroll
;                 for (int n = 0; n < 2; ++n)
; #pragma unroll
;                     for (int j = 0; j < 4; ++j) { const float gg = acc[ai][0][m][n][j] * rs, uu = acc[ai][1][m][n][j] * rs; h[4 * n + j] = siluf_(gg) * uu; }
;                 u32x4 w; w.x = cvt_pk(h[0], h[1]); w.y = cvt_pk(h[2], h[3]); w.z = cvt_pk(h[4], h[5]); w.w = cvt_pk(h[6], h[7]);
;                 *(u32x4*)(H + (size_t)row * DFF + col0) = w;
	v_mov_b32_e32 v17, v22
	v_pk_mul_f32 v[16:17], v[16:17], v[32:33] op_sel_hi:[1,0]
	v_mov_b32_e32 v22, v19
	v_mul_f32_e32 v18, 0xbfb8aa3b, v17
	v_exp_f32_e32 v18, v18
	s_nop 0
	v_add_f32_e32 v18, 1.0, v18
	v_rcp_f32_e32 v18, v18
	s_nop 0
	v_mul_f32_e32 v17, v17, v18
	v_mul_f32_e32 v21, v16, v17
	v_pk_mul_f32 v[16:17], v[22:23], v[32:33] op_sel_hi:[1,0]
	s_nop 0
	v_mul_f32_e32 v18, 0xbfb8aa3b, v17
	v_exp_f32_e32 v18, v18
	s_nop 0
	v_add_f32_e32 v18, 1.0, v18
	v_rcp_f32_e32 v18, v18
	s_nop 0
	v_mul_f32_e32 v17, v17, v18
	v_mul_f32_e32 v19, v16, v17
	v_cvt_pk_bf16_f32 v18, v24, v20
	v_cvt_pk_bf16_f32 v19, v21, v19
	v_mad_i64_i32 v[20:21], s[2:3], v33, s64, v[116:117]
	v_lshl_add_u64 v[20:21], v[20:21], 0, v[118:119]
	v_cvt_pk_bf16_f32 v16, v34, v28
	v_cvt_pk_bf16_f32 v17, v26, v27
	global_store_dwordx4 v[20:21], v[16:19], off
	s_nop 0
	s_nop 0
	v_add_u32_e32 v17, 0xb0, v138
	v_mov_b32_e32 v19, v12
	v_mov_b32_e32 v12, v9
	v_mov_b32_e32 v16, v168
	v_fmamk_f32 v16, v16, 0x3a800000, v217
	v_cmp_gt_f32_e32 vcc, s15, v16
	v_mul_f32_e32 v18, 0x4b800000, v16
	s_nop 0
	v_cndmask_b32_e32 v16, v16, v18, vcc
	v_rsq_f32_e32 v16, v16
	s_nop 0
	v_mul_f32_e32 v18, 0x45800000, v16
	v_cndmask_b32_e32 v16, v16, v18, vcc
	v_mov_b32_e32 v18, v8
	v_pk_mul_f32 v[18:19], v[18:19], v[16:17] op_sel_hi:[1,0]
	s_andn2_b64 vcc, exec, s[4:5]
	v_mul_f32_e32 v8, 0xbfb8aa3b, v19
	v_exp_f32_e32 v8, v8
	s_nop 0
	v_add_f32_e32 v8, 1.0, v8
	v_rcp_f32_e32 v8, v8
	s_nop 0
	v_mul_f32_e32 v8, v19, v8
	v_mul_f32_e32 v18, v18, v8
	v_pk_mul_f32 v[8:9], v[12:13], v[16:17] op_sel_hi:[1,0]
	s_nop 0
	v_mul_f32_e32 v12, 0xbfb8aa3b, v9
	v_exp_f32_e32 v12, v12
	s_nop 0
	v_add_f32_e32 v12, 1.0, v12
	v_rcp_f32_e32 v12, v12
	s_nop 0
	v_mul_f32_e32 v9, v9, v12
	v_mul_f32_e32 v12, v8, v9
	v_mov_b32_e32 v8, v10
	v_mov_b32_e32 v9, v14
	v_pk_mul_f32 v[8:9], v[8:9], v[16:17] op_sel_hi:[1,0]
	v_mov_b32_e32 v14, v11
	v_mul_f32_e32 v10, 0xbfb8aa3b, v9
	v_exp_f32_e32 v10, v10
	s_nop 0
	v_add_f32_e32 v10, 1.0, v10
	v_rcp_f32_e32 v10, v10
	s_nop 0
	v_mul_f32_e32 v9, v9, v10
	v_mul_f32_e32 v10, v8, v9
	v_pk_mul_f32 v[8:9], v[14:15], v[16:17] op_sel_hi:[1,0]
	s_nop 0
	v_mul_f32_e32 v11, 0xbfb8aa3b, v9
	v_exp_f32_e32 v11, v11
	s_nop 0
	v_add_f32_e32 v11, 1.0, v11
	v_rcp_f32_e32 v11, v11
	s_nop 0
	v_mul_f32_e32 v9, v9, v11
	v_mul_f32_e32 v11, v8, v9
	v_mov_b32_e32 v8, v0
	v_mov_b32_e32 v9, v4
	v_pk_mul_f32 v[8:9], v[8:9], v[16:17] op_sel_hi:[1,0]
	v_mov_b32_e32 v4, v1
	v_mul_f32_e32 v0, 0xbfb8aa3b, v9
	v_exp_f32_e32 v0, v0
	s_nop 0
	v_add_f32_e32 v0, 1.0, v0
	v_rcp_f32_e32 v0, v0
	s_nop 0
	v_mul_f32_e32 v0, v9, v0
	v_mul_f32_e32 v8, v8, v0
	v_pk_mul_f32 v[0:1], v[4:5], v[16:17] op_sel_hi:[1,0]
	s_nop 0
	v_mul_f32_e32 v4, 0xbfb8aa3b, v1
	v_exp_f32_e32 v4, v4
	s_nop 0
	v_add_f32_e32 v4, 1.0, v4
	v_rcp_f32_e32 v4, v4
	s_nop 0
	v_mul_f32_e32 v1, v1, v4
	v_mul_f32_e32 v4, v0, v1
	v_mov_b32_e32 v0, v2
	v_mov_b32_e32 v1, v6
	v_pk_mul_f32 v[0:1], v[0:1], v[16:17] op_sel_hi:[1,0]
	v_mov_b32_e32 v6, v3
	v_mul_f32_e32 v2, 0xbfb8aa3b, v1
	v_exp_f32_e32 v2, v2
	s_nop 0
	v_add_f32_e32 v2, 1.0, v2
	v_rcp_f32_e32 v2, v2
	s_nop 0
	v_mul_f32_e32 v1, v1, v2
	v_mul_f32_e32 v5, v0, v1
	v_pk_mul_f32 v[0:1], v[6:7], v[16:17] op_sel_hi:[1,0]
	s_nop 0
	v_mul_f32_e32 v2, 0xbfb8aa3b, v1
	v_exp_f32_e32 v2, v2
	s_nop 0
	v_add_f32_e32 v2, 1.0, v2
	v_rcp_f32_e32 v2, v2
	s_nop 0
	v_mul_f32_e32 v1, v1, v2
	v_mul_f32_e32 v3, v0, v1
	v_cvt_pk_bf16_f32 v2, v8, v4
	v_cvt_pk_bf16_f32 v3, v5, v3
	v_mad_i64_i32 v[4:5], s[2:3], v17, s64, v[116:117]
	v_lshl_add_u64 v[4:5], v[4:5], 0, v[118:119]
	s_mov_b64 s[2:3], -1
	v_cvt_pk_bf16_f32 v0, v18, v12
	v_cvt_pk_bf16_f32 v1, v10, v11
	global_store_dwordx4 v[4:5], v[0:3], off
	s_cbranch_vccnz .LBB0_286
	s_andn2_b64 vcc, exec, s[6:7]
	s_cbranch_vccnz .LBB0_285
	s_barrier
	s_branch .LBB0_285

; DI unsigned cvt_pk(float lo, float hi) { unsigned r; asm("v_cvt_pk_bf16_f32 %0, %1, %2" : "=v"(r) : "v"(lo), "v"(hi)); return r; }
;     __device__ __forceinline__ void operator()(const f32x4 (&acc)[2][2][4][2], const Unit& u, int wr, int wc, int fr, int fq) const {
;     ...
;             for (int m = 0; m < 4; ++m) {
;                 const int row = row0 + ai * HALF + m * 16;
;                 const float rs = rsqrtf(ss[row] * (1.f / DM) + EPS);
; #pragma unroll
;                 for (int bj = 0; bj < 2; ++bj) {
;                     const f32x4 v0 = acc[ai][bj][m][0] * rs, v1 = acc[ai][bj][m][1] * rs;
;                     u32x4 w; w.x = cvt_pk(v0[0], v0[1]); w.y = cvt_pk(v0[2], v0[3]); w.z = cvt_pk(v1[0], v1[1]); w.w = cvt_pk(v1[2], v1[3]);
;                     *(u32x4*)(O + (size_t)row * ldc + col0 + bj * HALF) = w;
;                 }
.LBB0_542:
	v_lshl_add_u32 v138, s39, 8, v142
	v_ashrrev_i32_e32 v139, 31, v138
	v_lshl_add_u64 v[140:141], v[138:139], 2, s[4:5]
	global_load_dword v139, v[140:141], off
	global_load_dword v162, v[140:141], off offset:64
	global_load_dword v163, v[140:141], off offset:128
	global_load_dword v164, v[140:141], off offset:192
	global_load_dword v165, v[140:141], off offset:512
	global_load_dword v166, v[140:141], off offset:576
	global_load_dword v167, v[140:141], off offset:640
	global_load_dword v168, v[140:141], off offset:704
	s_mov_b32 s11, 0x800000
	v_lshl_or_b32 v156, s38, 8, v154
	v_ashrrev_i32_e32 v157, 31, v156
	s_waitcnt vmcnt(0)
	v_fmamk_f32 v139, v139, 0x3a800000, v217
	v_cmp_gt_f32_e32 vcc, s11, v139
	v_mul_f32_e32 v158, 0x4b800000, v139
	s_nop 0
	v_cndmask_b32_e32 v139, v139, v158, vcc
	v_rsq_f32_e32 v139, v139
	s_nop 0
	v_mul_f32_e32 v158, 0x45800000, v139
	v_cndmask_b32_e32 v158, v139, v158, vcc
	v_pk_mul_f32 v[126:127], v[126:127], v[158:159] op_sel_hi:[1,0]
	v_pk_mul_f32 v[124:125], v[124:125], v[158:159] op_sel_hi:[1,0]
	v_pk_mul_f32 v[120:121], v[120:121], v[158:159] op_sel_hi:[1,0]
	v_pk_mul_f32 v[122:123], v[122:123], v[158:159] op_sel_hi:[1,0]
	v_cvt_pk_bf16_f32 v124, v124, v125
	v_cvt_pk_bf16_f32 v125, v126, v127
	v_cvt_pk_bf16_f32 v126, v120, v121
	v_mov_b64_e32 v[120:121], s[2:3]
	v_cvt_pk_bf16_f32 v127, v122, v123
	v_mad_i64_i32 v[160:161], s[20:21], v138, s64, v[120:121]
	v_lshlrev_b64 v[122:123], 1, v[156:157]
	v_lshl_add_u64 v[156:157], v[160:161], 0, v[122:123]
	global_store_dwordx4 v[156:157], v[124:127], off
	v_pk_mul_f32 v[118:119], v[118:119], v[158:159] op_sel_hi:[1,0]
	v_pk_mul_f32 v[116:117], v[116:117], v[158:159] op_sel_hi:[1,0]
	v_pk_mul_f32 v[124:125], v[114:115], v[158:159] op_sel_hi:[1,0]
	v_pk_mul_f32 v[114:115], v[112:113], v[158:159] op_sel_hi:[1,0]
	v_cvt_pk_bf16_f32 v112, v116, v117
	v_cvt_pk_bf16_f32 v113, v118, v119
	s_nop 0
	v_cvt_pk_bf16_f32 v114, v114, v115
	v_cvt_pk_bf16_f32 v115, v124, v125
	global_store_dwordx4 v[156:157], v[112:115], off offset:256
	s_nop 0
	s_nop 0
	v_or_b32_e32 v113, 16, v138
	v_mov_b32_e32 v112, v162
	v_fmamk_f32 v112, v112, 0x3a800000, v217
	v_cmp_gt_f32_e32 vcc, s11, v112
	v_mul_f32_e32 v114, 0x4b800000, v112
	s_nop 0
	v_cndmask_b32_e32 v112, v112, v114, vcc
	v_rsq_f32_e32 v112, v112
	s_nop 0
	v_mul_f32_e32 v114, 0x45800000, v112
	v_cndmask_b32_e32 v112, v112, v114, vcc
	v_pk_mul_f32 v[108:109], v[108:109], v[112:113] op_sel_hi:[1,0]
	v_pk_mul_f32 v[114:115], v[106:107], v[112:113] op_sel_hi:[1,0]
	v_pk_mul_f32 v[106:107], v[104:105], v[112:113] op_sel_hi:[1,0]
	v_cvt_pk_bf16_f32 v104, v108, v109
	v_mad_i64_i32 v[108:109], s[20:21], v113, s64, v[120:121]
	v_pk_mul_f32 v[110:111], v[110:111], v[112:113] op_sel_hi:[1,0]
	v_lshl_add_u64 v[108:109], v[108:109], 0, v[122:123]
	v_cvt_pk_bf16_f32 v105, v110, v111
	v_cvt_pk_bf16_f32 v106, v106, v107
	v_cvt_pk_bf16_f32 v107, v114, v115
	global_store_dwordx4 v[108:109], v[104:107], off
	v_pk_mul_f32 v[102:103], v[102:103], v[112:113] op_sel_hi:[1,0]
	v_pk_mul_f32 v[100:101], v[100:101], v[112:113] op_sel_hi:[1,0]
	v_pk_mul_f32 v[104:105], v[98:99], v[112:113] op_sel_hi:[1,0]
	v_pk_mul_f32 v[98:99], v[96:97], v[112:113] op_sel_hi:[1,0]
	v_cvt_pk_bf16_f32 v96, v100, v101
	v_cvt_pk_bf16_f32 v97, v102, v103
	s_nop 0
	v_cvt_pk_bf16_f32 v98, v98, v99
	v_cvt_pk_bf16_f32 v99, v104, v105
	global_store_dwordx4 v[108:109], v[96:99], off offset:256
	s_nop 0
	s_nop 0
	v_or_b32_e32 v97, 32, v138
	v_mov_b32_e32 v96, v163
	v_fmamk_f32 v96, v96, 0x3a800000, v217
	v_cmp_gt_f32_e32 vcc, s11, v96
	v_mul_f32_e32 v98, 0x4b800000, v96
	s_nop 0
	v_cndmask_b32_e32 v96, v96, v98, vcc
	v_rsq_f32_e32 v96, v96
	s_nop 0
	v_mul_f32_e32 v98, 0x45800000, v96
	v_cndmask_b32_e32 v96, v96, v98, vcc
	v_pk_mul_f32 v[92:93], v[92:93], v[96:97] op_sel_hi:[1,0]
	v_pk_mul_f32 v[98:99], v[90:91], v[96:97] op_sel_hi:[1,0]
	v_pk_mul_f32 v[90:91], v[88:89], v[96:97] op_sel_hi:[1,0]
	v_cvt_pk_bf16_f32 v88, v92, v93
	v_mad_i64_i32 v[92:93], s[20:21], v97, s64, v[120:121]
	v_pk_mul_f32 v[94:95], v[94:95], v[96:97] op_sel_hi:[1,0]
	v_lshl_add_u64 v[92:93], v[92:93], 0, v[122:123]
	v_cvt_pk_bf16_f32 v89, v94, v95
	v_cvt_pk_bf16_f32 v90, v90, v91
	v_cvt_pk_bf16_f32 v91, v98, v99
	global_store_dwordx4 v[92:93], v[88:91], off
	v_pk_mul_f32 v[86:87], v[86:87], v[96:97] op_sel_hi:[1,0]
	v_pk_mul_f32 v[84:85], v[84:85], v[96:97] op_sel_hi:[1,0]
	v_pk_mul_f32 v[88:89], v[82:83], v[96:97] op_sel_hi:[1,0]
	v_pk_mul_f32 v[82:83], v[80:81], v[96:97] op_sel_hi:[1,0]
	v_cvt_pk_bf16_f32 v80, v84, v85
	v_cvt_pk_bf16_f32 v81, v86, v87
	s_nop 0
	v_cvt_pk_bf16_f32 v82, v82, v83
	v_cvt_pk_bf16_f32 v83, v88, v89
	global_store_dwordx4 v[92:93], v[80:83], off offset:256
	s_nop 0
	s_nop 0
	v_or_b32_e32 v81, 48, v138
	v_mov_b32_e32 v80, v164
	v_fmamk_f32 v80, v80, 0x3a800000, v217
	v_cmp_gt_f32_e32 vcc, s11, v80
	v_mul_f32_e32 v82, 0x4b800000, v80
	s_nop 0
	v_cndmask_b32_e32 v80, v80, v82, vcc
	v_rsq_f32_e32 v80, v80
	s_nop 0
	v_mul_f32_e32 v82, 0x45800000, v80
	v_cndmask_b32_e32 v80, v80, v82, vcc
	v_pk_mul_f32 v[76:77], v[76:77], v[80:81] op_sel_hi:[1,0]
	v_pk_mul_f32 v[82:83], v[74:75], v[80:81] op_sel_hi:[1,0]
	v_pk_mul_f32 v[74:75], v[72:73], v[80:81] op_sel_hi:[1,0]
	v_cvt_pk_bf16_f32 v72, v76, v77
	v_mad_i64_i32 v[76:77], s[20:21], v81, s64, v[120:121]
	v_pk_mul_f32 v[78:79], v[78:79], v[80:81] op_sel_hi:[1,0]
	v_lshl_add_u64 v[76:77], v[76:77], 0, v[122:123]
	v_cvt_pk_bf16_f32 v73, v78, v79
	v_cvt_pk_bf16_f32 v74, v74, v75
	v_cvt_pk_bf16_f32 v75, v82, v83
	global_store_dwordx4 v[76:77], v[72:75], off
	v_pk_mul_f32 v[70:71], v[70:71], v[80:81] op_sel_hi:[1,0]
; DI unsigned cvt_pk(float lo, float hi) { unsigned r; asm("v_cvt_pk_bf16_f32 %0, %1, %2" : "=v"(r) : "v"(lo), "v"(hi)); return r; }
; #define PG8_BAR __builtin_amdgcn_s_barrier()
; template <class Epi, class Sched, bool ALIGN_EPI = false, bool SP2 = false>
; __device__ __forceinline__ void gemm_phase(PG8_LAS unsigned char* lds, const Gemm g, const Sched& S, const Epi& E) {
;     ...
;         if constexpr (ALIGN_EPI) { if (wr == 0) PG8_BAR; }
;         E(acc, cur, wr, wc, fr, fq); S.done(cur);
;         if (!has_next) break;
; #pragma unroll
;         for (int a = 0; a < 2; ++a)
; #pragma unroll
;             for (int b = 0; b < 2; ++b)
; #pragma unroll
;                 for (int m = 0; m < 4; ++m)
; #pragma unroll
;                     for (int n = 0; n < 2; ++n) acc[a][b][m][n] = (f32x4){0.f, 0.f, 0.f, 0.f};
;         cur = nxt; cA = nA; cB = nB; ++ui;
;         if constexpr (ALIGN_EPI) { if (wr == 1) PG8_BAR; }
;     __device__ __forceinline__ void operator()(const f32x4 (&acc)[2][2][4][2], const Unit& u, int wr, int wc, int fr, int fq) const {
;     ...
;             for (int m = 0; m < 4; ++m) {
;                 const int row = row0 + ai * HALF + m * 16;
;                 const float rs = rsqrtf(ss[row] * (1.f / DM) + EPS);
; #pragma unroll
;                 for (int bj = 0; bj < 2; ++bj) {
;                     const f32x4 v0 = acc[ai][bj][m][0] * rs, v1 = acc[ai][bj][m][1] * rs;
;                     u32x4 w; w.x = cvt_pk(v0[0], v0[1]); w.y = cvt_pk(v0[2], v0[3]); w.z = cvt_pk(v1[0], v1[1]); w.w = cvt_pk(v1[2], v1[3]);
;                     *(u32x4*)(O + (size_t)row * ldc + col0 + bj * HALF) = w;
;                 }
	v_pk_mul_f32 v[68:69], v[68:69], v[80:81] op_sel_hi:[1,0]
	v_pk_mul_f32 v[72:73], v[66:67], v[80:81] op_sel_hi:[1,0]
	v_pk_mul_f32 v[66:67], v[64:65], v[80:81] op_sel_hi:[1,0]
	v_cvt_pk_bf16_f32 v64, v68, v69
	v_cvt_pk_bf16_f32 v65, v70, v71
	s_nop 0
	v_cvt_pk_bf16_f32 v66, v66, v67
	v_cvt_pk_bf16_f32 v67, v72, v73
	global_store_dwordx4 v[76:77], v[64:67], off offset:256
	s_nop 0
	s_nop 0
	v_add_u32_e32 v65, 0x80, v138
	v_mov_b32_e32 v64, v165
	v_fmamk_f32 v64, v64, 0x3a800000, v217
	v_cmp_gt_f32_e32 vcc, s11, v64
	v_mul_f32_e32 v66, 0x4b800000, v64
	s_nop 0
	v_cndmask_b32_e32 v64, v64, v66, vcc
	v_rsq_f32_e32 v64, v64
	s_nop 0
	v_mul_f32_e32 v66, 0x45800000, v64
	v_cndmask_b32_e32 v64, v64, v66, vcc
	v_pk_mul_f32 v[60:61], v[60:61], v[64:65] op_sel_hi:[1,0]
	v_pk_mul_f32 v[66:67], v[58:59], v[64:65] op_sel_hi:[1,0]
	v_pk_mul_f32 v[58:59], v[56:57], v[64:65] op_sel_hi:[1,0]
	v_cvt_pk_bf16_f32 v56, v60, v61
	v_mad_i64_i32 v[60:61], s[20:21], v65, s64, v[120:121]
	v_pk_mul_f32 v[62:63], v[62:63], v[64:65] op_sel_hi:[1,0]
	v_lshl_add_u64 v[60:61], v[60:61], 0, v[122:123]
	v_cvt_pk_bf16_f32 v57, v62, v63
	v_cvt_pk_bf16_f32 v58, v58, v59
	v_cvt_pk_bf16_f32 v59, v66, v67
	global_store_dwordx4 v[60:61], v[56:59], off
	v_pk_mul_f32 v[54:55], v[54:55], v[64:65] op_sel_hi:[1,0]
	v_pk_mul_f32 v[52:53], v[52:53], v[64:65] op_sel_hi:[1,0]
	v_pk_mul_f32 v[56:57], v[50:51], v[64:65] op_sel_hi:[1,0]
	v_pk_mul_f32 v[50:51], v[48:49], v[64:65] op_sel_hi:[1,0]
	v_cvt_pk_bf16_f32 v48, v52, v53
	v_cvt_pk_bf16_f32 v49, v54, v55
	s_nop 0
	v_cvt_pk_bf16_f32 v50, v50, v51
	v_cvt_pk_bf16_f32 v51, v56, v57
	global_store_dwordx4 v[60:61], v[48:51], off offset:256
	s_nop 0
	s_nop 0
	v_add_u32_e32 v49, 0x90, v138
	v_mov_b32_e32 v48, v166
	v_fmamk_f32 v48, v48, 0x3a800000, v217
	v_cmp_gt_f32_e32 vcc, s11, v48
	v_mul_f32_e32 v50, 0x4b800000, v48
	s_nop 0
	v_cndmask_b32_e32 v48, v48, v50, vcc
	v_rsq_f32_e32 v48, v48
	s_nop 0
	v_mul_f32_e32 v50, 0x45800000, v48
	v_cndmask_b32_e32 v48, v48, v50, vcc
	v_pk_mul_f32 v[44:45], v[44:45], v[48:49] op_sel_hi:[1,0]
	v_pk_mul_f32 v[50:51], v[42:43], v[48:49] op_sel_hi:[1,0]
	v_pk_mul_f32 v[42:43], v[40:41], v[48:49] op_sel_hi:[1,0]
	v_cvt_pk_bf16_f32 v40, v44, v45
	v_mad_i64_i32 v[44:45], s[20:21], v49, s64, v[120:121]
	v_pk_mul_f32 v[46:47], v[46:47], v[48:49] op_sel_hi:[1,0]
	v_lshl_add_u64 v[44:45], v[44:45], 0, v[122:123]
	v_cvt_pk_bf16_f32 v41, v46, v47
	v_cvt_pk_bf16_f32 v42, v42, v43
	v_cvt_pk_bf16_f32 v43, v50, v51
	global_store_dwordx4 v[44:45], v[40:43], off
	v_pk_mul_f32 v[38:39], v[38:39], v[48:49] op_sel_hi:[1,0]
	v_pk_mul_f32 v[36:37], v[36:37], v[48:49] op_sel_hi:[1,0]
	v_pk_mul_f32 v[40:41], v[34:35], v[48:49] op_sel_hi:[1,0]
	v_pk_mul_f32 v[34:35], v[32:33], v[48:49] op_sel_hi:[1,0]
	v_cvt_pk_bf16_f32 v32, v36, v37
	v_cvt_pk_bf16_f32 v33, v38, v39
	s_nop 0
	v_cvt_pk_bf16_f32 v34, v34, v35
	v_cvt_pk_bf16_f32 v35, v40, v41
	global_store_dwordx4 v[44:45], v[32:35], off offset:256
	s_nop 0
	s_nop 0
	v_add_u32_e32 v33, 0xa0, v138
	v_mov_b32_e32 v32, v167
	v_fmamk_f32 v32, v32, 0x3a800000, v217
	v_cmp_gt_f32_e32 vcc, s11, v32
	v_mul_f32_e32 v34, 0x4b800000, v32
	s_nop 0
	v_cndmask_b32_e32 v32, v32, v34, vcc
	v_rsq_f32_e32 v32, v32
	s_nop 0
	v_mul_f32_e32 v34, 0x45800000, v32
	v_cndmask_b32_e32 v32, v32, v34, vcc
	v_pk_mul_f32 v[28:29], v[28:29], v[32:33] op_sel_hi:[1,0]
	v_pk_mul_f32 v[34:35], v[26:27], v[32:33] op_sel_hi:[1,0]
	v_pk_mul_f32 v[26:27], v[24:25], v[32:33] op_sel_hi:[1,0]
	v_cvt_pk_bf16_f32 v24, v28, v29
	v_mad_i64_i32 v[28:29], s[20:21], v33, s64, v[120:121]
	v_pk_mul_f32 v[30:31], v[30:31], v[32:33] op_sel_hi:[1,0]
	v_lshl_add_u64 v[28:29], v[28:29], 0, v[122:123]
	v_cvt_pk_bf16_f32 v25, v30, v31
	v_cvt_pk_bf16_f32 v26, v26, v27
	v_cvt_pk_bf16_f32 v27, v34, v35
	global_store_dwordx4 v[28:29], v[24:27], off
	v_pk_mul_f32 v[22:23], v[22:23], v[32:33] op_sel_hi:[1,0]
	v_pk_mul_f32 v[20:21], v[20:21], v[32:33] op_sel_hi:[1,0]
	v_pk_mul_f32 v[24:25], v[18:19], v[32:33] op_sel_hi:[1,0]
	v_pk_mul_f32 v[18:19], v[16:17], v[32:33] op_sel_hi:[1,0]
	v_cvt_pk_bf16_f32 v16, v20, v21
	v_cvt_pk_bf16_f32 v17, v22, v23
	s_nop 0
	v_cvt_pk_bf16_f32 v18, v18, v19
	v_cvt_pk_bf16_f32 v19, v24, v25
	global_store_dwordx4 v[28:29], v[16:19], off offset:256
	s_nop 0
	s_nop 0
	v_add_u32_e32 v17, 0xb0, v138
	v_mov_b32_e32 v16, v168
	v_fmamk_f32 v16, v16, 0x3a800000, v217
	v_cmp_gt_f32_e32 vcc, s11, v16
	v_mul_f32_e32 v18, 0x4b800000, v16
	s_nop 0
	v_cndmask_b32_e32 v16, v16, v18, vcc
	v_rsq_f32_e32 v16, v16
	s_nop 0
	v_mul_f32_e32 v18, 0x45800000, v16
	v_cndmask_b32_e32 v16, v16, v18, vcc
	v_pk_mul_f32 v[12:13], v[12:13], v[16:17] op_sel_hi:[1,0]
	v_pk_mul_f32 v[18:19], v[10:11], v[16:17] op_sel_hi:[1,0]
	v_pk_mul_f32 v[10:11], v[8:9], v[16:17] op_sel_hi:[1,0]
	v_cvt_pk_bf16_f32 v8, v12, v13
	v_mad_i64_i32 v[12:13], s[20:21], v17, s64, v[120:121]
	v_pk_mul_f32 v[14:15], v[14:15], v[16:17] op_sel_hi:[1,0]
	v_lshl_add_u64 v[12:13], v[12:13], 0, v[122:123]
	v_cvt_pk_bf16_f32 v9, v14, v15
	v_cvt_pk_bf16_f32 v10, v10, v11
	v_cvt_pk_bf16_f32 v11, v18, v19
	global_store_dwordx4 v[12:13], v[8:11], off
	s_mov_b64 s[20:21], -1
	s_andn2_b64 vcc, exec, s[8:9]
	v_pk_mul_f32 v[8:9], v[2:3], v[16:17] op_sel_hi:[1,0]
	v_pk_mul_f32 v[2:3], v[0:1], v[16:17] op_sel_hi:[1,0]
	v_pk_mul_f32 v[6:7], v[6:7], v[16:17] op_sel_hi:[1,0]
	v_pk_mul_f32 v[4:5], v[4:5], v[16:17] op_sel_hi:[1,0]
	v_cvt_pk_bf16_f32 v1, v6, v7
	v_cvt_pk_bf16_f32 v2, v2, v3
	v_cvt_pk_bf16_f32 v3, v8, v9
	s_nop 0
	v_cvt_pk_bf16_f32 v0, v4, v5
	global_store_dwordx4 v[12:13], v[0:3], off offset:256
	s_cbranch_vccnz .LBB0_535
	s_andn2_b64 vcc, exec, s[18:19]
	s_cbranch_vccnz .LBB0_534
	s_barrier
	s_branch .LBB0_534

; DI unsigned cvt_pk(float lo, float hi) { unsigned r; asm("v_cvt_pk_bf16_f32 %0, %1, %2" : "=v"(r) : "v"(lo), "v"(hi)); return r; }
; DI void state_scan(KA a, int l) {
;     ...
;     for (int q = gt; q < NB * NH * 1024; q += NGT) {
;         const int e = (q & 1023) * 8, bh = q >> 10, b = bh >> 2, hd = bh & 3, dkk = e >> 7;
;         float S[8];
; #pragma unroll
;         for (int k = 0; k < 8; ++k) S[k] = 0.f;
; #pragma unroll 11
;         for (int c = 0; c < NCH; ++c) {
;             const int uu = b * NCH + c;
;             u32x4* p = (u32x4*)(SBh + (size_t)(uu * 4 + hd) * 8192 + e);
;             float uv[8]; unpack8(*p, uv);
;             const float d = db[(size_t)(uu * 4 + hd) * 64 + dkk];
;             u32x4 w; w.x = cvt_pk(S[0], S[1]); w.y = cvt_pk(S[2], S[3]); w.z = cvt_pk(S[4], S[5]); w.w = cvt_pk(S[6], S[7]);
;             *p = w;
; #pragma unroll
;             for (int k = 0; k < 8; ++k) S[k] = d * S[k] + uv[k];
;         }
.LBB0_730:
	v_lshlrev_b32_e32 v1, 3, v9
	v_and_b32_e32 v10, 0x1ff8, v1
	v_ashrrev_i32_e32 v22, 12, v9
	v_lshlrev_b32_e32 v144, 1, v10
	v_lshrrev_b32_e32 v2, 2, v9
	v_bfe_u32 v0, v9, 10, 2
	v_mul_i32_i24_e32 v1, 33, v22
	v_lshl_add_u64 v[12:13], s[6:7], 0, v[144:145]
	v_and_b32_e32 v144, 0xfc, v2
	v_mov_b32_e32 v2, 0
	v_lshrrev_b32_e32 v11, 10, v9
	v_lshl_add_u64 v[14:15], s[8:9], 0, v[144:145]
	v_lshl_or_b32 v23, v1, 2, v0
	s_mov_b32 s14, 0
	v_mov_b32_e32 v3, v2
	v_mov_b32_e32 v4, v2
	v_mov_b32_e32 v5, v2
	v_mov_b32_e32 v6, v2
	v_mov_b32_e32 v7, v2
	v_mov_b32_e32 v0, v2
	v_mov_b32_e32 v1, v2
	v_mov_b32_e32 v18, v2
	v_lshlrev_b32_e32 v197, 14, v23
	v_lshl_add_u32 v197, v10, 1, v197
	v_lshrrev_b32_e32 v198, 2, v9
	v_and_b32_e32 v198, 0xfc, v198
	v_lshl_add_u32 v198, v23, 8, v198
	v_mov_b32_e32 v3, v2
	s_mov_b64 s[26:27], s[6:7]
	s_mov_b64 s[28:29], s[8:9]
	s_mov_b64 s[32:33], s[6:7]
	global_load_dwordx4 v[38:41], v197, s[26:27]
	global_load_dword v50, v198, s[28:29]
	s_add_u32 s26, s26, 0x10000
	s_addc_u32 s27, s27, 0
	s_add_u32 s28, s28, 0x400
	s_addc_u32 s29, s29, 0
	global_load_dwordx4 v[42:45], v197, s[26:27]
	global_load_dword v51, v198, s[28:29]
	s_add_u32 s26, s26, 0x10000
	s_addc_u32 s27, s27, 0
	s_add_u32 s28, s28, 0x400
	s_addc_u32 s29, s29, 0
	global_load_dwordx4 v[46:49], v197, s[26:27]
	global_load_dword v52, v198, s[28:29]
	s_add_u32 s26, s26, 0x10000
	s_addc_u32 s27, s27, 0
	s_add_u32 s28, s28, 0x400
	s_addc_u32 s29, s29, 0
	global_load_dwordx4 v[90:93], v197, s[26:27]
	global_load_dword v142, v198, s[28:29]
	s_add_u32 s26, s26, 0x10000
	s_addc_u32 s27, s27, 0
	s_add_u32 s28, s28, 0x400
	s_addc_u32 s29, s29, 0
	global_load_dwordx4 v[94:97], v197, s[26:27]
	global_load_dword v143, v198, s[28:29]
	s_add_u32 s26, s26, 0x10000
	s_addc_u32 s27, s27, 0
	s_add_u32 s28, s28, 0x400
	s_addc_u32 s29, s29, 0
	global_load_dwordx4 v[98:101], v197, s[26:27]
	global_load_dword v180, v198, s[28:29]
	s_add_u32 s26, s26, 0x10000
	s_addc_u32 s27, s27, 0
	s_add_u32 s28, s28, 0x400
	s_addc_u32 s29, s29, 0
	global_load_dwordx4 v[102:105], v197, s[26:27]
	global_load_dword v181, v198, s[28:29]
	s_add_u32 s26, s26, 0x10000
	s_addc_u32 s27, s27, 0
	s_add_u32 s28, s28, 0x400
	s_addc_u32 s29, s29, 0
	global_load_dwordx4 v[106:109], v197, s[26:27]
	global_load_dword v182, v198, s[28:29]
	s_add_u32 s26, s26, 0x10000
	s_addc_u32 s27, s27, 0
	s_add_u32 s28, s28, 0x400
	s_addc_u32 s29, s29, 0
	global_load_dwordx4 v[110:113], v197, s[26:27]
	global_load_dword v183, v198, s[28:29]
	s_add_u32 s26, s26, 0x10000
	s_addc_u32 s27, s27, 0
	s_add_u32 s28, s28, 0x400
	s_addc_u32 s29, s29, 0
	global_load_dwordx4 v[114:117], v197, s[26:27]
	global_load_dword v184, v198, s[28:29]
	s_add_u32 s26, s26, 0x10000
	s_addc_u32 s27, s27, 0
	s_add_u32 s28, s28, 0x400
	s_addc_u32 s29, s29, 0
	global_load_dwordx4 v[118:121], v197, s[26:27]
	global_load_dword v185, v198, s[28:29]
	s_add_u32 s26, s26, 0x10000
	s_addc_u32 s27, s27, 0
	s_add_u32 s28, s28, 0x400
	s_addc_u32 s29, s29, 0
	global_load_dwordx4 v[122:125], v197, s[26:27]
	global_load_dword v186, v198, s[28:29]
	s_add_u32 s26, s26, 0x10000
	s_addc_u32 s27, s27, 0
	s_add_u32 s28, s28, 0x400
	s_addc_u32 s29, s29, 0
	global_load_dwordx4 v[126:129], v197, s[26:27]
	global_load_dword v187, v198, s[28:29]
	s_add_u32 s26, s26, 0x10000
	s_addc_u32 s27, s27, 0
	s_add_u32 s28, s28, 0x400
	s_addc_u32 s29, s29, 0
	global_load_dwordx4 v[130:133], v197, s[26:27]
	global_load_dword v188, v198, s[28:29]
	s_add_u32 s26, s26, 0x10000
	s_addc_u32 s27, s27, 0
	s_add_u32 s28, s28, 0x400
	s_addc_u32 s29, s29, 0
	global_load_dwordx4 v[134:137], v197, s[26:27]
	global_load_dword v189, v198, s[28:29]
	s_add_u32 s26, s26, 0x10000
	s_addc_u32 s27, s27, 0
	s_add_u32 s28, s28, 0x400
	s_addc_u32 s29, s29, 0
	global_load_dwordx4 v[138:141], v197, s[26:27]
	global_load_dword v190, v198, s[28:29]
	s_add_u32 s26, s26, 0x10000
	s_addc_u32 s27, s27, 0
	s_add_u32 s28, s28, 0x400
	s_addc_u32 s29, s29, 0
	global_load_dwordx4 v[154:157], v197, s[26:27]
	global_load_dword v191, v198, s[28:29]
	s_add_u32 s26, s26, 0x10000
	s_addc_u32 s27, s27, 0
	s_add_u32 s28, s28, 0x400
	s_addc_u32 s29, s29, 0
	global_load_dwordx4 v[158:161], v197, s[26:27]
	global_load_dword v192, v198, s[28:29]
	s_add_u32 s26, s26, 0x10000
	s_addc_u32 s27, s27, 0
	s_add_u32 s28, s28, 0x400
	s_addc_u32 s29, s29, 0
	global_load_dwordx4 v[162:165], v197, s[26:27]
	global_load_dword v193, v198, s[28:29]
	s_add_u32 s26, s26, 0x10000
	s_addc_u32 s27, s27, 0
	s_add_u32 s28, s28, 0x400
	s_addc_u32 s29, s29, 0
	global_load_dwordx4 v[166:169], v197, s[26:27]
	global_load_dword v194, v198, s[28:29]
	s_add_u32 s26, s26, 0x10000
	s_addc_u32 s27, s27, 0
	s_add_u32 s28, s28, 0x400
	s_addc_u32 s29, s29, 0
	global_load_dwordx4 v[172:175], v197, s[26:27]
	global_load_dword v195, v198, s[28:29]
	s_add_u32 s26, s26, 0x10000
	s_addc_u32 s27, s27, 0
	s_add_u32 s28, s28, 0x400
	s_addc_u32 s29, s29, 0
	global_load_dwordx4 v[176:179], v197, s[26:27]
	global_load_dword v196, v198, s[28:29]
	s_add_u32 s26, s26, 0x10000
	s_addc_u32 s27, s27, 0
	s_add_u32 s28, s28, 0x400
	s_addc_u32 s29, s29, 0
	v_cvt_pk_bf16_f32 v34, v4, v5
	v_cvt_pk_bf16_f32 v35, v6, v7
	v_cvt_pk_bf16_f32 v36, v0, v1
	v_cvt_pk_bf16_f32 v37, v2, v3
	global_store_dwordx4 v197, v[34:37], s[32:33]
	s_add_u32 s32, s32, 0x10000
	s_addc_u32 s33, s33, 0
	s_waitcnt vmcnt(43)
; DI unsigned cvt_pk(float lo, float hi) { unsigned r; asm("v_cvt_pk_bf16_f32 %0, %1, %2" : "=v"(r) : "v"(lo), "v"(hi)); return r; }
; DI void state_scan(KA a, int l) {
;     ...
;         for (int c = 0; c < NCH; ++c) {
;             const int uu = b * NCH + c;
;             u32x4* p = (u32x4*)(SBh + (size_t)(uu * 4 + hd) * 8192 + e);
;             float uv[8]; unpack8(*p, uv);
;             const float d = db[(size_t)(uu * 4 + hd) * 64 + dkk];
;             u32x4 w; w.x = cvt_pk(S[0], S[1]); w.y = cvt_pk(S[2], S[3]); w.z = cvt_pk(S[4], S[5]); w.w = cvt_pk(S[6], S[7]);
;             *p = w;
; #pragma unroll
;             for (int k = 0; k < 8; ++k) S[k] = d * S[k] + uv[k];
;         }
	v_lshlrev_b32_e32 v199, 16, v38
	v_and_b32_e32 v200, 0xffff0000, v38
	v_lshlrev_b32_e32 v201, 16, v39
	v_and_b32_e32 v202, 0xffff0000, v39
	v_lshlrev_b32_e32 v203, 16, v40
	v_and_b32_e32 v204, 0xffff0000, v40
	v_lshlrev_b32_e32 v205, 16, v41
	v_and_b32_e32 v206, 0xffff0000, v41
	v_fma_f32 v4, v4, v50, v199
	v_fma_f32 v5, v5, v50, v200
	v_fma_f32 v6, v6, v50, v201
	v_fma_f32 v7, v7, v50, v202
	v_fma_f32 v0, v0, v50, v203
	v_fma_f32 v1, v1, v50, v204
	v_fma_f32 v2, v2, v50, v205
	v_fma_f32 v3, v3, v50, v206
	v_cvt_pk_bf16_f32 v34, v4, v5
	v_cvt_pk_bf16_f32 v35, v6, v7
	v_cvt_pk_bf16_f32 v36, v0, v1
	v_cvt_pk_bf16_f32 v37, v2, v3
	global_store_dwordx4 v197, v[34:37], s[32:33]
	s_add_u32 s32, s32, 0x10000
	s_addc_u32 s33, s33, 0
	s_waitcnt vmcnt(42)
	v_lshlrev_b32_e32 v199, 16, v42
	v_and_b32_e32 v200, 0xffff0000, v42
	v_lshlrev_b32_e32 v201, 16, v43
	v_and_b32_e32 v202, 0xffff0000, v43
	v_lshlrev_b32_e32 v203, 16, v44
	v_and_b32_e32 v204, 0xffff0000, v44
	v_lshlrev_b32_e32 v205, 16, v45
	v_and_b32_e32 v206, 0xffff0000, v45
	v_fma_f32 v4, v4, v51, v199
	v_fma_f32 v5, v5, v51, v200
	v_fma_f32 v6, v6, v51, v201
	v_fma_f32 v7, v7, v51, v202
	v_fma_f32 v0, v0, v51, v203
	v_fma_f32 v1, v1, v51, v204
	v_fma_f32 v2, v2, v51, v205
	v_fma_f32 v3, v3, v51, v206
	v_cvt_pk_bf16_f32 v34, v4, v5
	v_cvt_pk_bf16_f32 v35, v6, v7
	v_cvt_pk_bf16_f32 v36, v0, v1
	v_cvt_pk_bf16_f32 v37, v2, v3
	global_store_dwordx4 v197, v[34:37], s[32:33]
	s_add_u32 s32, s32, 0x10000
	s_addc_u32 s33, s33, 0
	s_waitcnt vmcnt(41)
	v_lshlrev_b32_e32 v199, 16, v46
	v_and_b32_e32 v200, 0xffff0000, v46
	v_lshlrev_b32_e32 v201, 16, v47
	v_and_b32_e32 v202, 0xffff0000, v47
	v_lshlrev_b32_e32 v203, 16, v48
	v_and_b32_e32 v204, 0xffff0000, v48
	v_lshlrev_b32_e32 v205, 16, v49
	v_and_b32_e32 v206, 0xffff0000, v49
	v_fma_f32 v4, v4, v52, v199
	v_fma_f32 v5, v5, v52, v200
	v_fma_f32 v6, v6, v52, v201
	v_fma_f32 v7, v7, v52, v202
	v_fma_f32 v0, v0, v52, v203
	v_fma_f32 v1, v1, v52, v204
	v_fma_f32 v2, v2, v52, v205
	v_fma_f32 v3, v3, v52, v206
	v_cvt_pk_bf16_f32 v34, v4, v5
	v_cvt_pk_bf16_f32 v35, v6, v7
	v_cvt_pk_bf16_f32 v36, v0, v1
	v_cvt_pk_bf16_f32 v37, v2, v3
	global_store_dwordx4 v197, v[34:37], s[32:33]
	s_add_u32 s32, s32, 0x10000
	s_addc_u32 s33, s33, 0
	s_waitcnt vmcnt(40)
	v_lshlrev_b32_e32 v199, 16, v90
	v_and_b32_e32 v200, 0xffff0000, v90
	v_lshlrev_b32_e32 v201, 16, v91
	v_and_b32_e32 v202, 0xffff0000, v91
	v_lshlrev_b32_e32 v203, 16, v92
	v_and_b32_e32 v204, 0xffff0000, v92
	v_lshlrev_b32_e32 v205, 16, v93
	v_and_b32_e32 v206, 0xffff0000, v93
	v_fma_f32 v4, v4, v142, v199
	v_fma_f32 v5, v5, v142, v200
	v_fma_f32 v6, v6, v142, v201
	v_fma_f32 v7, v7, v142, v202
	v_fma_f32 v0, v0, v142, v203
	v_fma_f32 v1, v1, v142, v204
	v_fma_f32 v2, v2, v142, v205
	v_fma_f32 v3, v3, v142, v206
	v_cvt_pk_bf16_f32 v34, v4, v5
	v_cvt_pk_bf16_f32 v35, v6, v7
	v_cvt_pk_bf16_f32 v36, v0, v1
	v_cvt_pk_bf16_f32 v37, v2, v3
	global_store_dwordx4 v197, v[34:37], s[32:33]
	s_add_u32 s32, s32, 0x10000
	s_addc_u32 s33, s33, 0
	s_waitcnt vmcnt(39)
	v_lshlrev_b32_e32 v199, 16, v94
	v_and_b32_e32 v200, 0xffff0000, v94
	v_lshlrev_b32_e32 v201, 16, v95
	v_and_b32_e32 v202, 0xffff0000, v95
	v_lshlrev_b32_e32 v203, 16, v96
	v_and_b32_e32 v204, 0xffff0000, v96
	v_lshlrev_b32_e32 v205, 16, v97
	v_and_b32_e32 v206, 0xffff0000, v97
	v_fma_f32 v4, v4, v143, v199
	v_fma_f32 v5, v5, v143, v200
	v_fma_f32 v6, v6, v143, v201
	v_fma_f32 v7, v7, v143, v202
	v_fma_f32 v0, v0, v143, v203
	v_fma_f32 v1, v1, v143, v204
	v_fma_f32 v2, v2, v143, v205
	v_fma_f32 v3, v3, v143, v206
	v_cvt_pk_bf16_f32 v34, v4, v5
	v_cvt_pk_bf16_f32 v35, v6, v7
	v_cvt_pk_bf16_f32 v36, v0, v1
	v_cvt_pk_bf16_f32 v37, v2, v3
	global_store_dwordx4 v197, v[34:37], s[32:33]
	s_add_u32 s32, s32, 0x10000
	s_addc_u32 s33, s33, 0
	s_waitcnt vmcnt(38)
	v_lshlrev_b32_e32 v199, 16, v98
	v_and_b32_e32 v200, 0xffff0000, v98
	v_lshlrev_b32_e32 v201, 16, v99
	v_and_b32_e32 v202, 0xffff0000, v99
	v_lshlrev_b32_e32 v203, 16, v100
	v_and_b32_e32 v204, 0xffff0000, v100
	v_lshlrev_b32_e32 v205, 16, v101
	v_and_b32_e32 v206, 0xffff0000, v101
	v_fma_f32 v4, v4, v180, v199
	v_fma_f32 v5, v5, v180, v200
	v_fma_f32 v6, v6, v180, v201
	v_fma_f32 v7, v7, v180, v202
	v_fma_f32 v0, v0, v180, v203
	v_fma_f32 v1, v1, v180, v204
	v_fma_f32 v2, v2, v180, v205
	v_fma_f32 v3, v3, v180, v206
	v_cvt_pk_bf16_f32 v34, v4, v5
	v_cvt_pk_bf16_f32 v35, v6, v7
	v_cvt_pk_bf16_f32 v36, v0, v1
	v_cvt_pk_bf16_f32 v37, v2, v3
	global_store_dwordx4 v197, v[34:37], s[32:33]
	s_add_u32 s32, s32, 0x10000
	s_addc_u32 s33, s33, 0
	s_waitcnt vmcnt(37)
	v_lshlrev_b32_e32 v199, 16, v102
	v_and_b32_e32 v200, 0xffff0000, v102
	v_lshlrev_b32_e32 v201, 16, v103
	v_and_b32_e32 v202, 0xffff0000, v103
	v_lshlrev_b32_e32 v203, 16, v104
	v_and_b32_e32 v204, 0xffff0000, v104
	v_lshlrev_b32_e32 v205, 16, v105
	v_and_b32_e32 v206, 0xffff0000, v105
	v_fma_f32 v4, v4, v181, v199
	v_fma_f32 v5, v5, v181, v200
	v_fma_f32 v6, v6, v181, v201
	v_fma_f32 v7, v7, v181, v202
	v_fma_f32 v0, v0, v181, v203
	v_fma_f32 v1, v1, v181, v204
	v_fma_f32 v2, v2, v181, v205
	v_fma_f32 v3, v3, v181, v206
	v_cvt_pk_bf16_f32 v34, v4, v5
	v_cvt_pk_bf16_f32 v35, v6, v7
	v_cvt_pk_bf16_f32 v36, v0, v1
	v_cvt_pk_bf16_f32 v37, v2, v3
	global_store_dwordx4 v197, v[34:37], s[32:33]
	s_add_u32 s32, s32, 0x10000
	s_addc_u32 s33, s33, 0
	s_waitcnt vmcnt(36)
; DI unsigned cvt_pk(float lo, float hi) { unsigned r; asm("v_cvt_pk_bf16_f32 %0, %1, %2" : "=v"(r) : "v"(lo), "v"(hi)); return r; }
; DI void state_scan(KA a, int l) {
;     ...
;         for (int c = 0; c < NCH; ++c) {
;             const int uu = b * NCH + c;
;             u32x4* p = (u32x4*)(SBh + (size_t)(uu * 4 + hd) * 8192 + e);
;             float uv[8]; unpack8(*p, uv);
;             const float d = db[(size_t)(uu * 4 + hd) * 64 + dkk];
;             u32x4 w; w.x = cvt_pk(S[0], S[1]); w.y = cvt_pk(S[2], S[3]); w.z = cvt_pk(S[4], S[5]); w.w = cvt_pk(S[6], S[7]);
;             *p = w;
; #pragma unroll
;             for (int k = 0; k < 8; ++k) S[k] = d * S[k] + uv[k];
;         }
	v_lshlrev_b32_e32 v199, 16, v106
	v_and_b32_e32 v200, 0xffff0000, v106
	v_lshlrev_b32_e32 v201, 16, v107
	v_and_b32_e32 v202, 0xffff0000, v107
	v_lshlrev_b32_e32 v203, 16, v108
	v_and_b32_e32 v204, 0xffff0000, v108
	v_lshlrev_b32_e32 v205, 16, v109
	v_and_b32_e32 v206, 0xffff0000, v109
	v_fma_f32 v4, v4, v182, v199
	v_fma_f32 v5, v5, v182, v200
	v_fma_f32 v6, v6, v182, v201
	v_fma_f32 v7, v7, v182, v202
	v_fma_f32 v0, v0, v182, v203
	v_fma_f32 v1, v1, v182, v204
	v_fma_f32 v2, v2, v182, v205
	v_fma_f32 v3, v3, v182, v206
	v_cvt_pk_bf16_f32 v34, v4, v5
	v_cvt_pk_bf16_f32 v35, v6, v7
	v_cvt_pk_bf16_f32 v36, v0, v1
	v_cvt_pk_bf16_f32 v37, v2, v3
	global_store_dwordx4 v197, v[34:37], s[32:33]
	s_add_u32 s32, s32, 0x10000
	s_addc_u32 s33, s33, 0
	s_waitcnt vmcnt(35)
	v_lshlrev_b32_e32 v199, 16, v110
	v_and_b32_e32 v200, 0xffff0000, v110
	v_lshlrev_b32_e32 v201, 16, v111
	v_and_b32_e32 v202, 0xffff0000, v111
	v_lshlrev_b32_e32 v203, 16, v112
	v_and_b32_e32 v204, 0xffff0000, v112
	v_lshlrev_b32_e32 v205, 16, v113
	v_and_b32_e32 v206, 0xffff0000, v113
	v_fma_f32 v4, v4, v183, v199
	v_fma_f32 v5, v5, v183, v200
	v_fma_f32 v6, v6, v183, v201
	v_fma_f32 v7, v7, v183, v202
	v_fma_f32 v0, v0, v183, v203
	v_fma_f32 v1, v1, v183, v204
	v_fma_f32 v2, v2, v183, v205
	v_fma_f32 v3, v3, v183, v206
	v_cvt_pk_bf16_f32 v34, v4, v5
	v_cvt_pk_bf16_f32 v35, v6, v7
	v_cvt_pk_bf16_f32 v36, v0, v1
	v_cvt_pk_bf16_f32 v37, v2, v3
	global_store_dwordx4 v197, v[34:37], s[32:33]
	s_add_u32 s32, s32, 0x10000
	s_addc_u32 s33, s33, 0
	s_waitcnt vmcnt(34)
	v_lshlrev_b32_e32 v199, 16, v114
	v_and_b32_e32 v200, 0xffff0000, v114
	v_lshlrev_b32_e32 v201, 16, v115
	v_and_b32_e32 v202, 0xffff0000, v115
	v_lshlrev_b32_e32 v203, 16, v116
	v_and_b32_e32 v204, 0xffff0000, v116
	v_lshlrev_b32_e32 v205, 16, v117
	v_and_b32_e32 v206, 0xffff0000, v117
	v_fma_f32 v4, v4, v184, v199
	v_fma_f32 v5, v5, v184, v200
	v_fma_f32 v6, v6, v184, v201
	v_fma_f32 v7, v7, v184, v202
	v_fma_f32 v0, v0, v184, v203
	v_fma_f32 v1, v1, v184, v204
	v_fma_f32 v2, v2, v184, v205
	v_fma_f32 v3, v3, v184, v206
	v_cvt_pk_bf16_f32 v34, v4, v5
	v_cvt_pk_bf16_f32 v35, v6, v7
	v_cvt_pk_bf16_f32 v36, v0, v1
	v_cvt_pk_bf16_f32 v37, v2, v3
	global_store_dwordx4 v197, v[34:37], s[32:33]
	s_add_u32 s32, s32, 0x10000
	s_addc_u32 s33, s33, 0
	s_waitcnt vmcnt(33)
	v_lshlrev_b32_e32 v199, 16, v118
	v_and_b32_e32 v200, 0xffff0000, v118
	v_lshlrev_b32_e32 v201, 16, v119
	v_and_b32_e32 v202, 0xffff0000, v119
	v_lshlrev_b32_e32 v203, 16, v120
	v_and_b32_e32 v204, 0xffff0000, v120
	v_lshlrev_b32_e32 v205, 16, v121
	v_and_b32_e32 v206, 0xffff0000, v121
	v_fma_f32 v4, v4, v185, v199
	v_fma_f32 v5, v5, v185, v200
	v_fma_f32 v6, v6, v185, v201
	v_fma_f32 v7, v7, v185, v202
	v_fma_f32 v0, v0, v185, v203
	v_fma_f32 v1, v1, v185, v204
	v_fma_f32 v2, v2, v185, v205
	v_fma_f32 v3, v3, v185, v206
	global_load_dwordx4 v[38:41], v197, s[26:27]
	global_load_dword v50, v198, s[28:29]
	s_add_u32 s26, s26, 0x10000
	s_addc_u32 s27, s27, 0
	s_add_u32 s28, s28, 0x400
	s_addc_u32 s29, s29, 0
	global_load_dwordx4 v[42:45], v197, s[26:27]
	global_load_dword v51, v198, s[28:29]
	s_add_u32 s26, s26, 0x10000
	s_addc_u32 s27, s27, 0
	s_add_u32 s28, s28, 0x400
	s_addc_u32 s29, s29, 0
	global_load_dwordx4 v[46:49], v197, s[26:27]
	global_load_dword v52, v198, s[28:29]
	s_add_u32 s26, s26, 0x10000
	s_addc_u32 s27, s27, 0
	s_add_u32 s28, s28, 0x400
	s_addc_u32 s29, s29, 0
	global_load_dwordx4 v[90:93], v197, s[26:27]
	global_load_dword v142, v198, s[28:29]
	s_add_u32 s26, s26, 0x10000
	s_addc_u32 s27, s27, 0
	s_add_u32 s28, s28, 0x400
	s_addc_u32 s29, s29, 0
	global_load_dwordx4 v[94:97], v197, s[26:27]
	global_load_dword v143, v198, s[28:29]
	s_add_u32 s26, s26, 0x10000
	s_addc_u32 s27, s27, 0
	s_add_u32 s28, s28, 0x400
	s_addc_u32 s29, s29, 0
	global_load_dwordx4 v[98:101], v197, s[26:27]
	global_load_dword v180, v198, s[28:29]
	s_add_u32 s26, s26, 0x10000
	s_addc_u32 s27, s27, 0
	s_add_u32 s28, s28, 0x400
	s_addc_u32 s29, s29, 0
	global_load_dwordx4 v[102:105], v197, s[26:27]
	global_load_dword v181, v198, s[28:29]
	s_add_u32 s26, s26, 0x10000
	s_addc_u32 s27, s27, 0
	s_add_u32 s28, s28, 0x400
	s_addc_u32 s29, s29, 0
	global_load_dwordx4 v[106:109], v197, s[26:27]
	global_load_dword v182, v198, s[28:29]
	s_add_u32 s26, s26, 0x10000
	s_addc_u32 s27, s27, 0
	s_add_u32 s28, s28, 0x400
	s_addc_u32 s29, s29, 0
	global_load_dwordx4 v[110:113], v197, s[26:27]
	global_load_dword v183, v198, s[28:29]
	s_add_u32 s26, s26, 0x10000
	s_addc_u32 s27, s27, 0
	s_add_u32 s28, s28, 0x400
	s_addc_u32 s29, s29, 0
	global_load_dwordx4 v[114:117], v197, s[26:27]
	global_load_dword v184, v198, s[28:29]
	s_add_u32 s26, s26, 0x10000
	s_addc_u32 s27, s27, 0
	s_add_u32 s28, s28, 0x400
	s_addc_u32 s29, s29, 0
	global_load_dwordx4 v[118:121], v197, s[26:27]
	global_load_dword v185, v198, s[28:29]
	s_add_u32 s26, s26, 0x10000
	s_addc_u32 s27, s27, 0
	s_add_u32 s28, s28, 0x400
	s_addc_u32 s29, s29, 0
	v_cvt_pk_bf16_f32 v34, v4, v5
	v_cvt_pk_bf16_f32 v35, v6, v7
	v_cvt_pk_bf16_f32 v36, v0, v1
	v_cvt_pk_bf16_f32 v37, v2, v3
	global_store_dwordx4 v197, v[34:37], s[32:33]
	s_add_u32 s32, s32, 0x10000
	s_addc_u32 s33, s33, 0
	s_waitcnt vmcnt(54)
	v_lshlrev_b32_e32 v199, 16, v122
	v_and_b32_e32 v200, 0xffff0000, v122
	v_lshlrev_b32_e32 v201, 16, v123
	v_and_b32_e32 v202, 0xffff0000, v123
	v_lshlrev_b32_e32 v203, 16, v124
	v_and_b32_e32 v204, 0xffff0000, v124
	v_lshlrev_b32_e32 v205, 16, v125
	v_and_b32_e32 v206, 0xffff0000, v125
	v_fma_f32 v4, v4, v186, v199
	v_fma_f32 v5, v5, v186, v200
	v_fma_f32 v6, v6, v186, v201
	v_fma_f32 v7, v7, v186, v202
	v_fma_f32 v0, v0, v186, v203
	v_fma_f32 v1, v1, v186, v204
	v_fma_f32 v2, v2, v186, v205
	v_fma_f32 v3, v3, v186, v206
	v_cvt_pk_bf16_f32 v34, v4, v5
	v_cvt_pk_bf16_f32 v35, v6, v7
	v_cvt_pk_bf16_f32 v36, v0, v1
	v_cvt_pk_bf16_f32 v37, v2, v3
	global_store_dwordx4 v197, v[34:37], s[32:33]
	s_add_u32 s32, s32, 0x10000
	s_addc_u32 s33, s33, 0
	s_waitcnt vmcnt(53)
; DI unsigned cvt_pk(float lo, float hi) { unsigned r; asm("v_cvt_pk_bf16_f32 %0, %1, %2" : "=v"(r) : "v"(lo), "v"(hi)); return r; }
; DI void state_scan(KA a, int l) {
;     ...
;         for (int c = 0; c < NCH; ++c) {
;             const int uu = b * NCH + c;
;             u32x4* p = (u32x4*)(SBh + (size_t)(uu * 4 + hd) * 8192 + e);
;             float uv[8]; unpack8(*p, uv);
;             const float d = db[(size_t)(uu * 4 + hd) * 64 + dkk];
;             u32x4 w; w.x = cvt_pk(S[0], S[1]); w.y = cvt_pk(S[2], S[3]); w.z = cvt_pk(S[4], S[5]); w.w = cvt_pk(S[6], S[7]);
;             *p = w;
; #pragma unroll
;             for (int k = 0; k < 8; ++k) S[k] = d * S[k] + uv[k];
;         }
	v_lshlrev_b32_e32 v199, 16, v126
	v_and_b32_e32 v200, 0xffff0000, v126
	v_lshlrev_b32_e32 v201, 16, v127
	v_and_b32_e32 v202, 0xffff0000, v127
	v_lshlrev_b32_e32 v203, 16, v128
	v_and_b32_e32 v204, 0xffff0000, v128
	v_lshlrev_b32_e32 v205, 16, v129
	v_and_b32_e32 v206, 0xffff0000, v129
	v_fma_f32 v4, v4, v187, v199
	v_fma_f32 v5, v5, v187, v200
	v_fma_f32 v6, v6, v187, v201
	v_fma_f32 v7, v7, v187, v202
	v_fma_f32 v0, v0, v187, v203
	v_fma_f32 v1, v1, v187, v204
	v_fma_f32 v2, v2, v187, v205
	v_fma_f32 v3, v3, v187, v206
	v_cvt_pk_bf16_f32 v34, v4, v5
	v_cvt_pk_bf16_f32 v35, v6, v7
	v_cvt_pk_bf16_f32 v36, v0, v1
	v_cvt_pk_bf16_f32 v37, v2, v3
	global_store_dwordx4 v197, v[34:37], s[32:33]
	s_add_u32 s32, s32, 0x10000
	s_addc_u32 s33, s33, 0
	s_waitcnt vmcnt(52)
	v_lshlrev_b32_e32 v199, 16, v130
	v_and_b32_e32 v200, 0xffff0000, v130
	v_lshlrev_b32_e32 v201, 16, v131
	v_and_b32_e32 v202, 0xffff0000, v131
	v_lshlrev_b32_e32 v203, 16, v132
	v_and_b32_e32 v204, 0xffff0000, v132
	v_lshlrev_b32_e32 v205, 16, v133
	v_and_b32_e32 v206, 0xffff0000, v133
	v_fma_f32 v4, v4, v188, v199
	v_fma_f32 v5, v5, v188, v200
	v_fma_f32 v6, v6, v188, v201
	v_fma_f32 v7, v7, v188, v202
	v_fma_f32 v0, v0, v188, v203
	v_fma_f32 v1, v1, v188, v204
	v_fma_f32 v2, v2, v188, v205
	v_fma_f32 v3, v3, v188, v206
	v_cvt_pk_bf16_f32 v34, v4, v5
	v_cvt_pk_bf16_f32 v35, v6, v7
	v_cvt_pk_bf16_f32 v36, v0, v1
	v_cvt_pk_bf16_f32 v37, v2, v3
	global_store_dwordx4 v197, v[34:37], s[32:33]
	s_add_u32 s32, s32, 0x10000
	s_addc_u32 s33, s33, 0
	s_waitcnt vmcnt(51)
	v_lshlrev_b32_e32 v199, 16, v134
	v_and_b32_e32 v200, 0xffff0000, v134
	v_lshlrev_b32_e32 v201, 16, v135
	v_and_b32_e32 v202, 0xffff0000, v135
	v_lshlrev_b32_e32 v203, 16, v136
	v_and_b32_e32 v204, 0xffff0000, v136
	v_lshlrev_b32_e32 v205, 16, v137
	v_and_b32_e32 v206, 0xffff0000, v137
	v_fma_f32 v4, v4, v189, v199
	v_fma_f32 v5, v5, v189, v200
	v_fma_f32 v6, v6, v189, v201
	v_fma_f32 v7, v7, v189, v202
	v_fma_f32 v0, v0, v189, v203
	v_fma_f32 v1, v1, v189, v204
	v_fma_f32 v2, v2, v189, v205
	v_fma_f32 v3, v3, v189, v206
	v_cvt_pk_bf16_f32 v34, v4, v5
	v_cvt_pk_bf16_f32 v35, v6, v7
	v_cvt_pk_bf16_f32 v36, v0, v1
	v_cvt_pk_bf16_f32 v37, v2, v3
	global_store_dwordx4 v197, v[34:37], s[32:33]
	s_add_u32 s32, s32, 0x10000
	s_addc_u32 s33, s33, 0
	s_waitcnt vmcnt(50)
	v_lshlrev_b32_e32 v199, 16, v138
	v_and_b32_e32 v200, 0xffff0000, v138
	v_lshlrev_b32_e32 v201, 16, v139
	v_and_b32_e32 v202, 0xffff0000, v139
	v_lshlrev_b32_e32 v203, 16, v140
	v_and_b32_e32 v204, 0xffff0000, v140
	v_lshlrev_b32_e32 v205, 16, v141
	v_and_b32_e32 v206, 0xffff0000, v141
	v_fma_f32 v4, v4, v190, v199
	v_fma_f32 v5, v5, v190, v200
	v_fma_f32 v6, v6, v190, v201
	v_fma_f32 v7, v7, v190, v202
	v_fma_f32 v0, v0, v190, v203
	v_fma_f32 v1, v1, v190, v204
	v_fma_f32 v2, v2, v190, v205
	v_fma_f32 v3, v3, v190, v206
	v_cvt_pk_bf16_f32 v34, v4, v5
	v_cvt_pk_bf16_f32 v35, v6, v7
	v_cvt_pk_bf16_f32 v36, v0, v1
	v_cvt_pk_bf16_f32 v37, v2, v3
	global_store_dwordx4 v197, v[34:37], s[32:33]
	s_add_u32 s32, s32, 0x10000
	s_addc_u32 s33, s33, 0
	s_waitcnt vmcnt(49)
	v_lshlrev_b32_e32 v199, 16, v154
	v_and_b32_e32 v200, 0xffff0000, v154
	v_lshlrev_b32_e32 v201, 16, v155
	v_and_b32_e32 v202, 0xffff0000, v155
	v_lshlrev_b32_e32 v203, 16, v156
	v_and_b32_e32 v204, 0xffff0000, v156
	v_lshlrev_b32_e32 v205, 16, v157
	v_and_b32_e32 v206, 0xffff0000, v157
	v_fma_f32 v4, v4, v191, v199
	v_fma_f32 v5, v5, v191, v200
	v_fma_f32 v6, v6, v191, v201
	v_fma_f32 v7, v7, v191, v202
	v_fma_f32 v0, v0, v191, v203
	v_fma_f32 v1, v1, v191, v204
	v_fma_f32 v2, v2, v191, v205
	v_fma_f32 v3, v3, v191, v206
	v_cvt_pk_bf16_f32 v34, v4, v5
	v_cvt_pk_bf16_f32 v35, v6, v7
	v_cvt_pk_bf16_f32 v36, v0, v1
	v_cvt_pk_bf16_f32 v37, v2, v3
	global_store_dwordx4 v197, v[34:37], s[32:33]
	s_add_u32 s32, s32, 0x10000
	s_addc_u32 s33, s33, 0
	s_waitcnt vmcnt(48)
	v_lshlrev_b32_e32 v199, 16, v158
	v_and_b32_e32 v200, 0xffff0000, v158
	v_lshlrev_b32_e32 v201, 16, v159
	v_and_b32_e32 v202, 0xffff0000, v159
	v_lshlrev_b32_e32 v203, 16, v160
	v_and_b32_e32 v204, 0xffff0000, v160
	v_lshlrev_b32_e32 v205, 16, v161
	v_and_b32_e32 v206, 0xffff0000, v161
	v_fma_f32 v4, v4, v192, v199
	v_fma_f32 v5, v5, v192, v200
	v_fma_f32 v6, v6, v192, v201
	v_fma_f32 v7, v7, v192, v202
	v_fma_f32 v0, v0, v192, v203
	v_fma_f32 v1, v1, v192, v204
	v_fma_f32 v2, v2, v192, v205
	v_fma_f32 v3, v3, v192, v206
	v_cvt_pk_bf16_f32 v34, v4, v5
	v_cvt_pk_bf16_f32 v35, v6, v7
	v_cvt_pk_bf16_f32 v36, v0, v1
	v_cvt_pk_bf16_f32 v37, v2, v3
	global_store_dwordx4 v197, v[34:37], s[32:33]
	s_add_u32 s32, s32, 0x10000
	s_addc_u32 s33, s33, 0
	s_waitcnt vmcnt(47)
	v_lshlrev_b32_e32 v199, 16, v162
	v_and_b32_e32 v200, 0xffff0000, v162
	v_lshlrev_b32_e32 v201, 16, v163
	v_and_b32_e32 v202, 0xffff0000, v163
	v_lshlrev_b32_e32 v203, 16, v164
	v_and_b32_e32 v204, 0xffff0000, v164
	v_lshlrev_b32_e32 v205, 16, v165
	v_and_b32_e32 v206, 0xffff0000, v165
	v_fma_f32 v4, v4, v193, v199
	v_fma_f32 v5, v5, v193, v200
	v_fma_f32 v6, v6, v193, v201
	v_fma_f32 v7, v7, v193, v202
	v_fma_f32 v0, v0, v193, v203
	v_fma_f32 v1, v1, v193, v204
	v_fma_f32 v2, v2, v193, v205
	v_fma_f32 v3, v3, v193, v206
	v_cvt_pk_bf16_f32 v34, v4, v5
	v_cvt_pk_bf16_f32 v35, v6, v7
	v_cvt_pk_bf16_f32 v36, v0, v1
	v_cvt_pk_bf16_f32 v37, v2, v3
	global_store_dwordx4 v197, v[34:37], s[32:33]
	s_add_u32 s32, s32, 0x10000
	s_addc_u32 s33, s33, 0
	s_waitcnt vmcnt(46)
; DI unsigned cvt_pk(float lo, float hi) { unsigned r; asm("v_cvt_pk_bf16_f32 %0, %1, %2" : "=v"(r) : "v"(lo), "v"(hi)); return r; }
; DI void state_scan(KA a, int l) {
;     ...
;         for (int c = 0; c < NCH; ++c) {
;             const int uu = b * NCH + c;
;             u32x4* p = (u32x4*)(SBh + (size_t)(uu * 4 + hd) * 8192 + e);
;             float uv[8]; unpack8(*p, uv);
;             const float d = db[(size_t)(uu * 4 + hd) * 64 + dkk];
;             u32x4 w; w.x = cvt_pk(S[0], S[1]); w.y = cvt_pk(S[2], S[3]); w.z = cvt_pk(S[4], S[5]); w.w = cvt_pk(S[6], S[7]);
;             *p = w;
; #pragma unroll
;             for (int k = 0; k < 8; ++k) S[k] = d * S[k] + uv[k];
;         }
	v_lshlrev_b32_e32 v199, 16, v166
	v_and_b32_e32 v200, 0xffff0000, v166
	v_lshlrev_b32_e32 v201, 16, v167
	v_and_b32_e32 v202, 0xffff0000, v167
	v_lshlrev_b32_e32 v203, 16, v168
	v_and_b32_e32 v204, 0xffff0000, v168
	v_lshlrev_b32_e32 v205, 16, v169
	v_and_b32_e32 v206, 0xffff0000, v169
	v_fma_f32 v4, v4, v194, v199
	v_fma_f32 v5, v5, v194, v200
	v_fma_f32 v6, v6, v194, v201
	v_fma_f32 v7, v7, v194, v202
	v_fma_f32 v0, v0, v194, v203
	v_fma_f32 v1, v1, v194, v204
	v_fma_f32 v2, v2, v194, v205
	v_fma_f32 v3, v3, v194, v206
	v_cvt_pk_bf16_f32 v34, v4, v5
	v_cvt_pk_bf16_f32 v35, v6, v7
	v_cvt_pk_bf16_f32 v36, v0, v1
	v_cvt_pk_bf16_f32 v37, v2, v3
	global_store_dwordx4 v197, v[34:37], s[32:33]
	s_add_u32 s32, s32, 0x10000
	s_addc_u32 s33, s33, 0
	s_waitcnt vmcnt(45)
	v_lshlrev_b32_e32 v199, 16, v172
	v_and_b32_e32 v200, 0xffff0000, v172
	v_lshlrev_b32_e32 v201, 16, v173
	v_and_b32_e32 v202, 0xffff0000, v173
	v_lshlrev_b32_e32 v203, 16, v174
	v_and_b32_e32 v204, 0xffff0000, v174
	v_lshlrev_b32_e32 v205, 16, v175
	v_and_b32_e32 v206, 0xffff0000, v175
	v_fma_f32 v4, v4, v195, v199
	v_fma_f32 v5, v5, v195, v200
	v_fma_f32 v6, v6, v195, v201
	v_fma_f32 v7, v7, v195, v202
	v_fma_f32 v0, v0, v195, v203
	v_fma_f32 v1, v1, v195, v204
	v_fma_f32 v2, v2, v195, v205
	v_fma_f32 v3, v3, v195, v206
	v_cvt_pk_bf16_f32 v34, v4, v5
	v_cvt_pk_bf16_f32 v35, v6, v7
	v_cvt_pk_bf16_f32 v36, v0, v1
	v_cvt_pk_bf16_f32 v37, v2, v3
	global_store_dwordx4 v197, v[34:37], s[32:33]
	s_add_u32 s32, s32, 0x10000
	s_addc_u32 s33, s33, 0
	s_waitcnt vmcnt(44)
	v_lshlrev_b32_e32 v199, 16, v176
	v_and_b32_e32 v200, 0xffff0000, v176
	v_lshlrev_b32_e32 v201, 16, v177
	v_and_b32_e32 v202, 0xffff0000, v177
	v_lshlrev_b32_e32 v203, 16, v178
	v_and_b32_e32 v204, 0xffff0000, v178
	v_lshlrev_b32_e32 v205, 16, v179
	v_and_b32_e32 v206, 0xffff0000, v179
	v_fma_f32 v4, v4, v196, v199
	v_fma_f32 v5, v5, v196, v200
	v_fma_f32 v6, v6, v196, v201
	v_fma_f32 v7, v7, v196, v202
	v_fma_f32 v0, v0, v196, v203
	v_fma_f32 v1, v1, v196, v204
	v_fma_f32 v2, v2, v196, v205
	v_fma_f32 v3, v3, v196, v206
	v_cvt_pk_bf16_f32 v34, v4, v5
	v_cvt_pk_bf16_f32 v35, v6, v7
	v_cvt_pk_bf16_f32 v36, v0, v1
	v_cvt_pk_bf16_f32 v37, v2, v3
	global_store_dwordx4 v197, v[34:37], s[32:33]
	s_add_u32 s32, s32, 0x10000
	s_addc_u32 s33, s33, 0
	s_waitcnt vmcnt(32)
	v_lshlrev_b32_e32 v199, 16, v38
	v_and_b32_e32 v200, 0xffff0000, v38
	v_lshlrev_b32_e32 v201, 16, v39
	v_and_b32_e32 v202, 0xffff0000, v39
	v_lshlrev_b32_e32 v203, 16, v40
	v_and_b32_e32 v204, 0xffff0000, v40
	v_lshlrev_b32_e32 v205, 16, v41
	v_and_b32_e32 v206, 0xffff0000, v41
	v_fma_f32 v4, v4, v50, v199
	v_fma_f32 v5, v5, v50, v200
	v_fma_f32 v6, v6, v50, v201
	v_fma_f32 v7, v7, v50, v202
	v_fma_f32 v0, v0, v50, v203
	v_fma_f32 v1, v1, v50, v204
	v_fma_f32 v2, v2, v50, v205
	v_fma_f32 v3, v3, v50, v206
	v_cvt_pk_bf16_f32 v34, v4, v5
	v_cvt_pk_bf16_f32 v35, v6, v7
	v_cvt_pk_bf16_f32 v36, v0, v1
	v_cvt_pk_bf16_f32 v37, v2, v3
	global_store_dwordx4 v197, v[34:37], s[32:33]
	s_add_u32 s32, s32, 0x10000
	s_addc_u32 s33, s33, 0
	s_waitcnt vmcnt(31)
	v_lshlrev_b32_e32 v199, 16, v42
	v_and_b32_e32 v200, 0xffff0000, v42
	v_lshlrev_b32_e32 v201, 16, v43
	v_and_b32_e32 v202, 0xffff0000, v43
	v_lshlrev_b32_e32 v203, 16, v44
	v_and_b32_e32 v204, 0xffff0000, v44
	v_lshlrev_b32_e32 v205, 16, v45
	v_and_b32_e32 v206, 0xffff0000, v45
	v_fma_f32 v4, v4, v51, v199
	v_fma_f32 v5, v5, v51, v200
	v_fma_f32 v6, v6, v51, v201
	v_fma_f32 v7, v7, v51, v202
	v_fma_f32 v0, v0, v51, v203
	v_fma_f32 v1, v1, v51, v204
	v_fma_f32 v2, v2, v51, v205
	v_fma_f32 v3, v3, v51, v206
	v_cvt_pk_bf16_f32 v34, v4, v5
	v_cvt_pk_bf16_f32 v35, v6, v7
	v_cvt_pk_bf16_f32 v36, v0, v1
	v_cvt_pk_bf16_f32 v37, v2, v3
	global_store_dwordx4 v197, v[34:37], s[32:33]
	s_add_u32 s32, s32, 0x10000
	s_addc_u32 s33, s33, 0
	s_waitcnt vmcnt(30)
	v_lshlrev_b32_e32 v199, 16, v46
	v_and_b32_e32 v200, 0xffff0000, v46
	v_lshlrev_b32_e32 v201, 16, v47
	v_and_b32_e32 v202, 0xffff0000, v47
	v_lshlrev_b32_e32 v203, 16, v48
	v_and_b32_e32 v204, 0xffff0000, v48
	v_lshlrev_b32_e32 v205, 16, v49
	v_and_b32_e32 v206, 0xffff0000, v49
	v_fma_f32 v4, v4, v52, v199
	v_fma_f32 v5, v5, v52, v200
	v_fma_f32 v6, v6, v52, v201
	v_fma_f32 v7, v7, v52, v202
	v_fma_f32 v0, v0, v52, v203
	v_fma_f32 v1, v1, v52, v204
	v_fma_f32 v2, v2, v52, v205
	v_fma_f32 v3, v3, v52, v206
	v_cvt_pk_bf16_f32 v34, v4, v5
	v_cvt_pk_bf16_f32 v35, v6, v7
	v_cvt_pk_bf16_f32 v36, v0, v1
	v_cvt_pk_bf16_f32 v37, v2, v3
	global_store_dwordx4 v197, v[34:37], s[32:33]
	s_add_u32 s32, s32, 0x10000
	s_addc_u32 s33, s33, 0
	s_waitcnt vmcnt(29)
	v_lshlrev_b32_e32 v199, 16, v90
	v_and_b32_e32 v200, 0xffff0000, v90
	v_lshlrev_b32_e32 v201, 16, v91
	v_and_b32_e32 v202, 0xffff0000, v91
	v_lshlrev_b32_e32 v203, 16, v92
	v_and_b32_e32 v204, 0xffff0000, v92
	v_lshlrev_b32_e32 v205, 16, v93
	v_and_b32_e32 v206, 0xffff0000, v93
	v_fma_f32 v4, v4, v142, v199
	v_fma_f32 v5, v5, v142, v200
	v_fma_f32 v6, v6, v142, v201
	v_fma_f32 v7, v7, v142, v202
	v_fma_f32 v0, v0, v142, v203
	v_fma_f32 v1, v1, v142, v204
	v_fma_f32 v2, v2, v142, v205
	v_fma_f32 v3, v3, v142, v206
	v_cvt_pk_bf16_f32 v34, v4, v5
	v_cvt_pk_bf16_f32 v35, v6, v7
	v_cvt_pk_bf16_f32 v36, v0, v1
	v_cvt_pk_bf16_f32 v37, v2, v3
	global_store_dwordx4 v197, v[34:37], s[32:33]
	s_add_u32 s32, s32, 0x10000
	s_addc_u32 s33, s33, 0
	s_waitcnt vmcnt(28)
; DI unsigned cvt_pk(float lo, float hi) { unsigned r; asm("v_cvt_pk_bf16_f32 %0, %1, %2" : "=v"(r) : "v"(lo), "v"(hi)); return r; }
; DI void state_scan(KA a, int l) {
;     ...
;     for (int q = gt; q < NB * NH * 1024; q += NGT) {
;     ...
;         for (int c = 0; c < NCH; ++c) {
;             const int uu = b * NCH + c;
;             u32x4* p = (u32x4*)(SBh + (size_t)(uu * 4 + hd) * 8192 + e);
;             float uv[8]; unpack8(*p, uv);
;             const float d = db[(size_t)(uu * 4 + hd) * 64 + dkk];
;             u32x4 w; w.x = cvt_pk(S[0], S[1]); w.y = cvt_pk(S[2], S[3]); w.z = cvt_pk(S[4], S[5]); w.w = cvt_pk(S[6], S[7]);
;             *p = w;
; #pragma unroll
;             for (int k = 0; k < 8; ++k) S[k] = d * S[k] + uv[k];
;         }
;         float* o = a->out + O_SP + (size_t)((l * NB + b) * 4 + hd) * 8192 + e;
;         *(f32x4*)o = (f32x4){S[0], S[1], S[2], S[3]}; *(f32x4*)(o + 4) = (f32x4){S[4], S[5], S[6], S[7]};
	v_lshlrev_b32_e32 v199, 16, v94
	v_and_b32_e32 v200, 0xffff0000, v94
	v_lshlrev_b32_e32 v201, 16, v95
	v_and_b32_e32 v202, 0xffff0000, v95
	v_lshlrev_b32_e32 v203, 16, v96
	v_and_b32_e32 v204, 0xffff0000, v96
	v_lshlrev_b32_e32 v205, 16, v97
	v_and_b32_e32 v206, 0xffff0000, v97
	v_fma_f32 v4, v4, v143, v199
	v_fma_f32 v5, v5, v143, v200
	v_fma_f32 v6, v6, v143, v201
	v_fma_f32 v7, v7, v143, v202
	v_fma_f32 v0, v0, v143, v203
	v_fma_f32 v1, v1, v143, v204
	v_fma_f32 v2, v2, v143, v205
	v_fma_f32 v3, v3, v143, v206
	v_cvt_pk_bf16_f32 v34, v4, v5
	v_cvt_pk_bf16_f32 v35, v6, v7
	v_cvt_pk_bf16_f32 v36, v0, v1
	v_cvt_pk_bf16_f32 v37, v2, v3
	global_store_dwordx4 v197, v[34:37], s[32:33]
	s_add_u32 s32, s32, 0x10000
	s_addc_u32 s33, s33, 0
	s_waitcnt vmcnt(27)
	v_lshlrev_b32_e32 v199, 16, v98
	v_and_b32_e32 v200, 0xffff0000, v98
	v_lshlrev_b32_e32 v201, 16, v99
	v_and_b32_e32 v202, 0xffff0000, v99
	v_lshlrev_b32_e32 v203, 16, v100
	v_and_b32_e32 v204, 0xffff0000, v100
	v_lshlrev_b32_e32 v205, 16, v101
	v_and_b32_e32 v206, 0xffff0000, v101
	v_fma_f32 v4, v4, v180, v199
	v_fma_f32 v5, v5, v180, v200
	v_fma_f32 v6, v6, v180, v201
	v_fma_f32 v7, v7, v180, v202
	v_fma_f32 v0, v0, v180, v203
	v_fma_f32 v1, v1, v180, v204
	v_fma_f32 v2, v2, v180, v205
	v_fma_f32 v3, v3, v180, v206
	v_cvt_pk_bf16_f32 v34, v4, v5
	v_cvt_pk_bf16_f32 v35, v6, v7
	v_cvt_pk_bf16_f32 v36, v0, v1
	v_cvt_pk_bf16_f32 v37, v2, v3
	global_store_dwordx4 v197, v[34:37], s[32:33]
	s_add_u32 s32, s32, 0x10000
	s_addc_u32 s33, s33, 0
	s_waitcnt vmcnt(26)
	v_lshlrev_b32_e32 v199, 16, v102
	v_and_b32_e32 v200, 0xffff0000, v102
	v_lshlrev_b32_e32 v201, 16, v103
	v_and_b32_e32 v202, 0xffff0000, v103
	v_lshlrev_b32_e32 v203, 16, v104
	v_and_b32_e32 v204, 0xffff0000, v104
	v_lshlrev_b32_e32 v205, 16, v105
	v_and_b32_e32 v206, 0xffff0000, v105
	v_fma_f32 v4, v4, v181, v199
	v_fma_f32 v5, v5, v181, v200
	v_fma_f32 v6, v6, v181, v201
	v_fma_f32 v7, v7, v181, v202
	v_fma_f32 v0, v0, v181, v203
	v_fma_f32 v1, v1, v181, v204
	v_fma_f32 v2, v2, v181, v205
	v_fma_f32 v3, v3, v181, v206
	v_cvt_pk_bf16_f32 v34, v4, v5
	v_cvt_pk_bf16_f32 v35, v6, v7
	v_cvt_pk_bf16_f32 v36, v0, v1
	v_cvt_pk_bf16_f32 v37, v2, v3
	global_store_dwordx4 v197, v[34:37], s[32:33]
	s_add_u32 s32, s32, 0x10000
	s_addc_u32 s33, s33, 0
	s_waitcnt vmcnt(25)
	v_lshlrev_b32_e32 v199, 16, v106
	v_and_b32_e32 v200, 0xffff0000, v106
	v_lshlrev_b32_e32 v201, 16, v107
	v_and_b32_e32 v202, 0xffff0000, v107
	v_lshlrev_b32_e32 v203, 16, v108
	v_and_b32_e32 v204, 0xffff0000, v108
	v_lshlrev_b32_e32 v205, 16, v109
	v_and_b32_e32 v206, 0xffff0000, v109
	v_fma_f32 v4, v4, v182, v199
	v_fma_f32 v5, v5, v182, v200
	v_fma_f32 v6, v6, v182, v201
	v_fma_f32 v7, v7, v182, v202
	v_fma_f32 v0, v0, v182, v203
	v_fma_f32 v1, v1, v182, v204
	v_fma_f32 v2, v2, v182, v205
	v_fma_f32 v3, v3, v182, v206
	v_cvt_pk_bf16_f32 v34, v4, v5
	v_cvt_pk_bf16_f32 v35, v6, v7
	v_cvt_pk_bf16_f32 v36, v0, v1
	v_cvt_pk_bf16_f32 v37, v2, v3
	global_store_dwordx4 v197, v[34:37], s[32:33]
	s_add_u32 s32, s32, 0x10000
	s_addc_u32 s33, s33, 0
	s_waitcnt vmcnt(24)
	v_lshlrev_b32_e32 v199, 16, v110
	v_and_b32_e32 v200, 0xffff0000, v110
	v_lshlrev_b32_e32 v201, 16, v111
	v_and_b32_e32 v202, 0xffff0000, v111
	v_lshlrev_b32_e32 v203, 16, v112
	v_and_b32_e32 v204, 0xffff0000, v112
	v_lshlrev_b32_e32 v205, 16, v113
	v_and_b32_e32 v206, 0xffff0000, v113
	v_fma_f32 v4, v4, v183, v199
	v_fma_f32 v5, v5, v183, v200
	v_fma_f32 v6, v6, v183, v201
	v_fma_f32 v7, v7, v183, v202
	v_fma_f32 v0, v0, v183, v203
	v_fma_f32 v1, v1, v183, v204
	v_fma_f32 v2, v2, v183, v205
	v_fma_f32 v3, v3, v183, v206
	v_cvt_pk_bf16_f32 v34, v4, v5
	v_cvt_pk_bf16_f32 v35, v6, v7
	v_cvt_pk_bf16_f32 v36, v0, v1
	v_cvt_pk_bf16_f32 v37, v2, v3
	global_store_dwordx4 v197, v[34:37], s[32:33]
	s_add_u32 s32, s32, 0x10000
	s_addc_u32 s33, s33, 0
	s_waitcnt vmcnt(23)
	v_lshlrev_b32_e32 v199, 16, v114
	v_and_b32_e32 v200, 0xffff0000, v114
	v_lshlrev_b32_e32 v201, 16, v115
	v_and_b32_e32 v202, 0xffff0000, v115
	v_lshlrev_b32_e32 v203, 16, v116
	v_and_b32_e32 v204, 0xffff0000, v116
	v_lshlrev_b32_e32 v205, 16, v117
	v_and_b32_e32 v206, 0xffff0000, v117
	v_fma_f32 v4, v4, v184, v199
	v_fma_f32 v5, v5, v184, v200
	v_fma_f32 v6, v6, v184, v201
	v_fma_f32 v7, v7, v184, v202
	v_fma_f32 v0, v0, v184, v203
	v_fma_f32 v1, v1, v184, v204
	v_fma_f32 v2, v2, v184, v205
	v_fma_f32 v3, v3, v184, v206
	v_cvt_pk_bf16_f32 v34, v4, v5
	v_cvt_pk_bf16_f32 v35, v6, v7
	v_cvt_pk_bf16_f32 v36, v0, v1
	v_cvt_pk_bf16_f32 v37, v2, v3
	global_store_dwordx4 v197, v[34:37], s[32:33]
	s_add_u32 s32, s32, 0x10000
	s_addc_u32 s33, s33, 0
	s_waitcnt vmcnt(22)
	v_lshlrev_b32_e32 v199, 16, v118
	v_and_b32_e32 v200, 0xffff0000, v118
	v_lshlrev_b32_e32 v201, 16, v119
	v_and_b32_e32 v202, 0xffff0000, v119
	v_lshlrev_b32_e32 v203, 16, v120
	v_and_b32_e32 v204, 0xffff0000, v120
	v_lshlrev_b32_e32 v205, 16, v121
	v_and_b32_e32 v206, 0xffff0000, v121
	v_fma_f32 v4, v4, v185, v199
	v_fma_f32 v5, v5, v185, v200
	v_fma_f32 v6, v6, v185, v201
	v_fma_f32 v7, v7, v185, v202
	v_fma_f32 v0, v0, v185, v203
	v_fma_f32 v1, v1, v185, v204
	v_fma_f32 v2, v2, v185, v205
	v_fma_f32 v3, v3, v185, v206
	s_load_dwordx2 s[14:15], s[2:3], 0xd0
	v_lshl_add_u32 v12, v22, 2, s0
	v_and_or_b32 v12, v11, 3, v12
	v_ashrrev_i32_e32 v13, 31, v12
	v_lshlrev_b64 v[12:13], 15, v[12:13]
	s_waitcnt lgkmcnt(0)
	v_lshl_add_u64 v[12:13], s[14:15], 0, v[12:13]
	v_lshlrev_b32_e32 v144, 2, v10
	v_lshl_add_u64 v[10:11], v[12:13], 0, v[144:145]
	s_mov_b64 s[14:15], 0x4420000
	v_lshl_add_u64 v[12:13], v[10:11], 0, s[14:15]
	v_add_co_u32_e32 v10, vcc, 0x4420000, v10
	v_readlane_b32 s14, v254, 54
	s_nop 0
	v_addc_co_u32_e32 v11, vcc, 0, v11, vcc
	v_add_u32_e32 v9, s14, v9
	s_movk_i32 s14, 0x7fff
	v_cmp_lt_i32_e32 vcc, s14, v9
	s_or_b64 s[10:11], vcc, s[10:11]
	global_store_dwordx4 v[10:11], v[4:7], off
	v_readlane_b32 s15, v254, 55
	global_store_dwordx4 v[12:13], v[0:3], off offset:16
	s_andn2_b64 exec, exec, s[10:11]
	s_cbranch_execnz .LBB0_730

; DI unsigned cvt_pk(float lo, float hi) { unsigned r; asm("v_cvt_pk_bf16_f32 %0, %1, %2" : "=v"(r) : "v"(lo), "v"(hi)); return r; }
; DI float siluf_(float x) { return x * sigmoidf_(x); }
;     __device__ __forceinline__ void operator()(const f32x4 (&acc)[2][2][4][2], const Unit& u, int wr, int wc, int fr, int fq) const {
;         const int row0 = u.pm * BM + wr * 64 + fr, col0 = u.pn * 128 + wc * 32 + 8 * fq;
; #pragma unroll
;         for (int ai = 0; ai < 2; ++ai)
; #pragma unroll
;             for (int m = 0; m < 4; ++m) {
;                 const int row = row0 + ai * HALF + m * 16;
;                 const float rs = rsqrtf(ss[row] * (1.f / DM) + EPS);
;                 float h[8];
; #pragma unroll
;                 for (int n = 0; n < 2; ++n)
; #pragma unroll
;                     for (int j = 0; j < 4; ++j) { const float gg = acc[ai][0][m][n][j] * rs, uu = acc[ai][1][m][n][j] * rs; h[4 * n + j] = siluf_(gg) * uu; }
;                 u32x4 w; w.x = cvt_pk(h[0], h[1]); w.y = cvt_pk(h[2], h[3]); w.z = cvt_pk(h[4], h[5]); w.w = cvt_pk(h[6], h[7]);
;                 *(u32x4*)(H + (size_t)row * DFF + col0) = w;
.LBB0_1298:
	v_lshl_add_u32 v138, s41, 8, v155
	v_ashrrev_i32_e32 v139, 31, v138
	v_lshl_add_u64 v[140:141], v[138:139], 2, s[10:11]
	global_load_dword v139, v[140:141], off
	global_load_dword v162, v[140:141], off offset:64
	global_load_dword v163, v[140:141], off offset:128
	global_load_dword v164, v[140:141], off offset:192
	global_load_dword v165, v[140:141], off offset:512
	global_load_dword v166, v[140:141], off offset:576
	global_load_dword v167, v[140:141], off offset:640
	global_load_dword v168, v[140:141], off offset:704
	s_mov_b32 s15, 0x800000
	v_mov_b32_e32 v160, v120
	v_mov_b32_e32 v161, v124
	v_mov_b32_e32 v124, v121
	v_lshl_or_b32 v142, s40, 7, v157
	v_ashrrev_i32_e32 v143, 31, v142
	s_waitcnt vmcnt(0)
	v_fmamk_f32 v139, v139, 0x3a800000, v217
	v_cmp_gt_f32_e32 vcc, s15, v139
	v_mul_f32_e32 v154, 0x4b800000, v139
	s_nop 0
	v_cndmask_b32_e32 v139, v139, v154, vcc
	v_rsq_f32_e32 v139, v139
	s_nop 0
	v_mul_f32_e32 v154, 0x45800000, v139
	v_cndmask_b32_e32 v154, v139, v154, vcc
	v_pk_mul_f32 v[160:161], v[160:161], v[154:155] op_sel_hi:[1,0]
	s_nop 0
	v_mul_f32_e32 v120, 0xbfb8aa3b, v161
	v_exp_f32_e32 v120, v120
	s_nop 0
	v_add_f32_e32 v120, 1.0, v120
	v_rcp_f32_e32 v120, v120
	s_nop 0
	v_mul_f32_e32 v120, v161, v120
	v_mul_f32_e32 v139, v160, v120
	v_pk_mul_f32 v[120:121], v[124:125], v[154:155] op_sel_hi:[1,0]
	s_nop 0
	v_mul_f32_e32 v124, 0xbfb8aa3b, v121
	v_exp_f32_e32 v124, v124
	s_nop 0
	v_add_f32_e32 v124, 1.0, v124
	v_rcp_f32_e32 v124, v124
	s_nop 0
	v_mul_f32_e32 v121, v121, v124
	v_mul_f32_e32 v124, v120, v121
	v_mov_b32_e32 v120, v122
	v_mov_b32_e32 v121, v126
	v_pk_mul_f32 v[120:121], v[120:121], v[154:155] op_sel_hi:[1,0]
	v_mov_b32_e32 v126, v123
	v_mul_f32_e32 v122, 0xbfb8aa3b, v121
	v_exp_f32_e32 v122, v122
	s_nop 0
	v_add_f32_e32 v122, 1.0, v122
	v_rcp_f32_e32 v122, v122
	s_nop 0
	v_mul_f32_e32 v121, v121, v122
	v_mul_f32_e32 v122, v120, v121
	v_pk_mul_f32 v[120:121], v[126:127], v[154:155] op_sel_hi:[1,0]
	s_nop 0
	v_mul_f32_e32 v123, 0xbfb8aa3b, v121
	v_exp_f32_e32 v123, v123
	s_nop 0
	v_add_f32_e32 v123, 1.0, v123
	v_rcp_f32_e32 v123, v123
	s_nop 0
	v_mul_f32_e32 v121, v121, v123
	v_mul_f32_e32 v123, v120, v121
	v_mov_b32_e32 v120, v112
	v_mov_b32_e32 v121, v116
	v_pk_mul_f32 v[120:121], v[120:121], v[154:155] op_sel_hi:[1,0]
	v_mov_b32_e32 v116, v113
	v_mul_f32_e32 v112, 0xbfb8aa3b, v121
	v_exp_f32_e32 v112, v112
	s_nop 0
	v_add_f32_e32 v112, 1.0, v112
	v_rcp_f32_e32 v112, v112
	s_nop 0
	v_mul_f32_e32 v112, v121, v112
	v_mul_f32_e32 v120, v120, v112
	v_pk_mul_f32 v[112:113], v[116:117], v[154:155] op_sel_hi:[1,0]
	s_nop 0
	v_mul_f32_e32 v116, 0xbfb8aa3b, v113
	v_exp_f32_e32 v116, v116
	s_nop 0
	v_add_f32_e32 v116, 1.0, v116
	v_rcp_f32_e32 v116, v116
	s_nop 0
	v_mul_f32_e32 v113, v113, v116
	v_mul_f32_e32 v116, v112, v113
	v_mov_b32_e32 v112, v114
	v_mov_b32_e32 v113, v118
	v_pk_mul_f32 v[112:113], v[112:113], v[154:155] op_sel_hi:[1,0]
	v_mov_b32_e32 v118, v115
	v_mul_f32_e32 v114, 0xbfb8aa3b, v113
	v_exp_f32_e32 v114, v114
	s_nop 0
	v_add_f32_e32 v114, 1.0, v114
	v_rcp_f32_e32 v114, v114
	s_nop 0
	v_mul_f32_e32 v113, v113, v114
	v_mul_f32_e32 v117, v112, v113
	v_pk_mul_f32 v[112:113], v[118:119], v[154:155] op_sel_hi:[1,0]
	v_lshlrev_b64 v[118:119], 1, v[142:143]
	v_mul_f32_e32 v114, 0xbfb8aa3b, v113
	v_exp_f32_e32 v114, v114
	s_nop 0
	v_add_f32_e32 v114, 1.0, v114
	v_rcp_f32_e32 v114, v114
	s_nop 0
	v_mul_f32_e32 v113, v113, v114
	v_mul_f32_e32 v115, v112, v113
	v_cvt_pk_bf16_f32 v114, v120, v116
	v_cvt_pk_bf16_f32 v115, v117, v115
	v_mov_b64_e32 v[116:117], s[4:5]
	v_mad_i64_i32 v[120:121], s[22:23], v138, s64, v[116:117]
	v_lshl_add_u64 v[120:121], v[120:121], 0, v[118:119]
	v_cvt_pk_bf16_f32 v112, v139, v124
	v_cvt_pk_bf16_f32 v113, v122, v123
	global_store_dwordx4 v[120:121], v[112:115], off
	s_nop 0
	s_nop 0
	v_or_b32_e32 v113, 16, v138
	v_mov_b32_e32 v115, v108
	v_mov_b32_e32 v108, v105
	v_mov_b32_e32 v112, v162
	v_fmamk_f32 v112, v112, 0x3a800000, v217
	v_cmp_gt_f32_e32 vcc, s15, v112
	v_mul_f32_e32 v114, 0x4b800000, v112
	s_nop 0
	v_cndmask_b32_e32 v112, v112, v114, vcc
	v_rsq_f32_e32 v112, v112
	s_nop 0
	v_mul_f32_e32 v114, 0x45800000, v112
	v_cndmask_b32_e32 v112, v112, v114, vcc
	v_mov_b32_e32 v114, v104
	v_pk_mul_f32 v[114:115], v[114:115], v[112:113] op_sel_hi:[1,0]
	s_nop 0
	v_mul_f32_e32 v104, 0xbfb8aa3b, v115
	v_exp_f32_e32 v104, v104
	s_nop 0
	v_add_f32_e32 v104, 1.0, v104
	v_rcp_f32_e32 v104, v104
	s_nop 0
	v_mul_f32_e32 v104, v115, v104
	v_mul_f32_e32 v114, v114, v104
	v_pk_mul_f32 v[104:105], v[108:109], v[112:113] op_sel_hi:[1,0]
	s_nop 0
	v_mul_f32_e32 v108, 0xbfb8aa3b, v105
	v_exp_f32_e32 v108, v108
	s_nop 0
	v_add_f32_e32 v108, 1.0, v108
	v_rcp_f32_e32 v108, v108
	s_nop 0
	v_mul_f32_e32 v105, v105, v108
	v_mul_f32_e32 v108, v104, v105
	v_mov_b32_e32 v104, v106
	v_mov_b32_e32 v105, v110
	v_pk_mul_f32 v[104:105], v[104:105], v[112:113] op_sel_hi:[1,0]
	v_mov_b32_e32 v110, v107
	v_mul_f32_e32 v106, 0xbfb8aa3b, v105
	v_exp_f32_e32 v106, v106
	s_nop 0
	v_add_f32_e32 v106, 1.0, v106
	v_rcp_f32_e32 v106, v106
	s_nop 0
	v_mul_f32_e32 v105, v105, v106
	v_mul_f32_e32 v106, v104, v105
	v_pk_mul_f32 v[104:105], v[110:111], v[112:113] op_sel_hi:[1,0]
	s_nop 0
	v_mul_f32_e32 v107, 0xbfb8aa3b, v105
	v_exp_f32_e32 v107, v107
	s_nop 0
	v_add_f32_e32 v107, 1.0, v107
	v_rcp_f32_e32 v107, v107
	s_nop 0
	v_mul_f32_e32 v105, v105, v107
	v_mul_f32_e32 v107, v104, v105
	v_mov_b32_e32 v104, v96
	v_mov_b32_e32 v105, v100
	v_pk_mul_f32 v[104:105], v[104:105], v[112:113] op_sel_hi:[1,0]
	v_mov_b32_e32 v100, v97
	v_mul_f32_e32 v96, 0xbfb8aa3b, v105
	v_exp_f32_e32 v96, v96
	s_nop 0
	v_add_f32_e32 v96, 1.0, v96
; DI unsigned cvt_pk(float lo, float hi) { unsigned r; asm("v_cvt_pk_bf16_f32 %0, %1, %2" : "=v"(r) : "v"(lo), "v"(hi)); return r; }
; DI float siluf_(float x) { return x * sigmoidf_(x); }
;     __device__ __forceinline__ void operator()(const f32x4 (&acc)[2][2][4][2], const Unit& u, int wr, int wc, int fr, int fq) const {
;     ...
;                 const int row = row0 + ai * HALF + m * 16;
;                 const float rs = rsqrtf(ss[row] * (1.f / DM) + EPS);
;                 float h[8];
; #pragma unroll
;                 for (int n = 0; n < 2; ++n)
; #pragma unroll
;                     for (int j = 0; j < 4; ++j) { const float gg = acc[ai][0][m][n][j] * rs, uu = acc[ai][1][m][n][j] * rs; h[4 * n + j] = siluf_(gg) * uu; }
;                 u32x4 w; w.x = cvt_pk(h[0], h[1]); w.y = cvt_pk(h[2], h[3]); w.z = cvt_pk(h[4], h[5]); w.w = cvt_pk(h[6], h[7]);
;                 *(u32x4*)(H + (size_t)row * DFF + col0) = w;
	v_rcp_f32_e32 v96, v96
	s_nop 0
	v_mul_f32_e32 v96, v105, v96
	v_mul_f32_e32 v104, v104, v96
	v_pk_mul_f32 v[96:97], v[100:101], v[112:113] op_sel_hi:[1,0]
	s_nop 0
	v_mul_f32_e32 v100, 0xbfb8aa3b, v97
	v_exp_f32_e32 v100, v100
	s_nop 0
	v_add_f32_e32 v100, 1.0, v100
	v_rcp_f32_e32 v100, v100
	s_nop 0
	v_mul_f32_e32 v97, v97, v100
	v_mul_f32_e32 v100, v96, v97
	v_mov_b32_e32 v96, v98
	v_mov_b32_e32 v97, v102
	v_pk_mul_f32 v[96:97], v[96:97], v[112:113] op_sel_hi:[1,0]
	v_mov_b32_e32 v102, v99
	v_mul_f32_e32 v98, 0xbfb8aa3b, v97
	v_exp_f32_e32 v98, v98
	s_nop 0
	v_add_f32_e32 v98, 1.0, v98
	v_rcp_f32_e32 v98, v98
	s_nop 0
	v_mul_f32_e32 v97, v97, v98
	v_mul_f32_e32 v101, v96, v97
	v_pk_mul_f32 v[96:97], v[102:103], v[112:113] op_sel_hi:[1,0]
	s_nop 0
	v_mul_f32_e32 v98, 0xbfb8aa3b, v97
	v_exp_f32_e32 v98, v98
	s_nop 0
	v_add_f32_e32 v98, 1.0, v98
	v_rcp_f32_e32 v98, v98
	s_nop 0
	v_mul_f32_e32 v97, v97, v98
	v_mul_f32_e32 v99, v96, v97
	v_cvt_pk_bf16_f32 v98, v104, v100
	v_cvt_pk_bf16_f32 v99, v101, v99
	v_mad_i64_i32 v[100:101], s[22:23], v113, s64, v[116:117]
	v_lshl_add_u64 v[100:101], v[100:101], 0, v[118:119]
	v_cvt_pk_bf16_f32 v96, v114, v108
	v_cvt_pk_bf16_f32 v97, v106, v107
	global_store_dwordx4 v[100:101], v[96:99], off
	s_nop 0
	s_nop 0
	v_or_b32_e32 v97, 32, v138
	v_mov_b32_e32 v99, v92
	v_mov_b32_e32 v92, v89
	v_mov_b32_e32 v96, v163
	v_fmamk_f32 v96, v96, 0x3a800000, v217
	v_cmp_gt_f32_e32 vcc, s15, v96
	v_mul_f32_e32 v98, 0x4b800000, v96
	s_nop 0
	v_cndmask_b32_e32 v96, v96, v98, vcc
	v_rsq_f32_e32 v96, v96
	s_nop 0
	v_mul_f32_e32 v98, 0x45800000, v96
	v_cndmask_b32_e32 v96, v96, v98, vcc
	v_mov_b32_e32 v98, v88
	v_pk_mul_f32 v[98:99], v[98:99], v[96:97] op_sel_hi:[1,0]
	s_nop 0
	v_mul_f32_e32 v88, 0xbfb8aa3b, v99
	v_exp_f32_e32 v88, v88
	s_nop 0
	v_add_f32_e32 v88, 1.0, v88
	v_rcp_f32_e32 v88, v88
	s_nop 0
	v_mul_f32_e32 v88, v99, v88
	v_mul_f32_e32 v98, v98, v88
	v_pk_mul_f32 v[88:89], v[92:93], v[96:97] op_sel_hi:[1,0]
	s_nop 0
	v_mul_f32_e32 v92, 0xbfb8aa3b, v89
	v_exp_f32_e32 v92, v92
	s_nop 0
	v_add_f32_e32 v92, 1.0, v92
	v_rcp_f32_e32 v92, v92
	s_nop 0
	v_mul_f32_e32 v89, v89, v92
	v_mul_f32_e32 v92, v88, v89
	v_mov_b32_e32 v88, v90
	v_mov_b32_e32 v89, v94
	v_pk_mul_f32 v[88:89], v[88:89], v[96:97] op_sel_hi:[1,0]
	v_mov_b32_e32 v94, v91
	v_mul_f32_e32 v90, 0xbfb8aa3b, v89
	v_exp_f32_e32 v90, v90
	s_nop 0
	v_add_f32_e32 v90, 1.0, v90
	v_rcp_f32_e32 v90, v90
	s_nop 0
	v_mul_f32_e32 v89, v89, v90
	v_mul_f32_e32 v90, v88, v89
	v_pk_mul_f32 v[88:89], v[94:95], v[96:97] op_sel_hi:[1,0]
	s_nop 0
	v_mul_f32_e32 v91, 0xbfb8aa3b, v89
	v_exp_f32_e32 v91, v91
	s_nop 0
	v_add_f32_e32 v91, 1.0, v91
	v_rcp_f32_e32 v91, v91
	s_nop 0
	v_mul_f32_e32 v89, v89, v91
	v_mul_f32_e32 v91, v88, v89
	v_mov_b32_e32 v88, v80
	v_mov_b32_e32 v89, v84
	v_pk_mul_f32 v[88:89], v[88:89], v[96:97] op_sel_hi:[1,0]
	v_mov_b32_e32 v84, v81
	v_mul_f32_e32 v80, 0xbfb8aa3b, v89
	v_exp_f32_e32 v80, v80
	s_nop 0
	v_add_f32_e32 v80, 1.0, v80
	v_rcp_f32_e32 v80, v80
	s_nop 0
	v_mul_f32_e32 v80, v89, v80
	v_mul_f32_e32 v88, v88, v80
	v_pk_mul_f32 v[80:81], v[84:85], v[96:97] op_sel_hi:[1,0]
	s_nop 0
	v_mul_f32_e32 v84, 0xbfb8aa3b, v81
	v_exp_f32_e32 v84, v84
	s_nop 0
	v_add_f32_e32 v84, 1.0, v84
	v_rcp_f32_e32 v84, v84
	s_nop 0
	v_mul_f32_e32 v81, v81, v84
	v_mul_f32_e32 v84, v80, v81
	v_mov_b32_e32 v80, v82
	v_mov_b32_e32 v81, v86
	v_pk_mul_f32 v[80:81], v[80:81], v[96:97] op_sel_hi:[1,0]
	v_mov_b32_e32 v86, v83
	v_mul_f32_e32 v82, 0xbfb8aa3b, v81
	v_exp_f32_e32 v82, v82
	s_nop 0
	v_add_f32_e32 v82, 1.0, v82
	v_rcp_f32_e32 v82, v82
	s_nop 0
	v_mul_f32_e32 v81, v81, v82
	v_mul_f32_e32 v85, v80, v81
	v_pk_mul_f32 v[80:81], v[86:87], v[96:97] op_sel_hi:[1,0]
	s_nop 0
	v_mul_f32_e32 v82, 0xbfb8aa3b, v81
	v_exp_f32_e32 v82, v82
	s_nop 0
	v_add_f32_e32 v82, 1.0, v82
	v_rcp_f32_e32 v82, v82
	s_nop 0
	v_mul_f32_e32 v81, v81, v82
	v_mul_f32_e32 v83, v80, v81
	v_cvt_pk_bf16_f32 v82, v88, v84
	v_cvt_pk_bf16_f32 v83, v85, v83
	v_mad_i64_i32 v[84:85], s[22:23], v97, s64, v[116:117]
	v_lshl_add_u64 v[84:85], v[84:85], 0, v[118:119]
	v_cvt_pk_bf16_f32 v80, v98, v92
	v_cvt_pk_bf16_f32 v81, v90, v91
	global_store_dwordx4 v[84:85], v[80:83], off
	s_nop 0
	s_nop 0
	v_or_b32_e32 v81, 48, v138
	v_mov_b32_e32 v83, v76
	v_mov_b32_e32 v76, v73
	v_mov_b32_e32 v80, v164
	v_fmamk_f32 v80, v80, 0x3a800000, v217
	v_cmp_gt_f32_e32 vcc, s15, v80
	v_mul_f32_e32 v82, 0x4b800000, v80
	s_nop 0
	v_cndmask_b32_e32 v80, v80, v82, vcc
	v_rsq_f32_e32 v80, v80
	s_nop 0
	v_mul_f32_e32 v82, 0x45800000, v80
	v_cndmask_b32_e32 v80, v80, v82, vcc
	v_mov_b32_e32 v82, v72
	v_pk_mul_f32 v[82:83], v[82:83], v[80:81] op_sel_hi:[1,0]
	s_nop 0
	v_mul_f32_e32 v72, 0xbfb8aa3b, v83
	v_exp_f32_e32 v72, v72
	s_nop 0
	v_add_f32_e32 v72, 1.0, v72
	v_rcp_f32_e32 v72, v72
	s_nop 0
	v_mul_f32_e32 v72, v83, v72
	v_mul_f32_e32 v82, v82, v72
	v_pk_mul_f32 v[72:73], v[76:77], v[80:81] op_sel_hi:[1,0]
	s_nop 0
	v_mul_f32_e32 v76, 0xbfb8aa3b, v73
	v_exp_f32_e32 v76, v76
	s_nop 0
	v_add_f32_e32 v76, 1.0, v76
	v_rcp_f32_e32 v76, v76
	s_nop 0
	v_mul_f32_e32 v73, v73, v76
	v_mul_f32_e32 v76, v72, v73
	v_mov_b32_e32 v72, v74
	v_mov_b32_e32 v73, v78
	v_pk_mul_f32 v[72:73], v[72:73], v[80:81] op_sel_hi:[1,0]
	v_mov_b32_e32 v78, v75
	v_mul_f32_e32 v74, 0xbfb8aa3b, v73
	v_exp_f32_e32 v74, v74
	s_nop 0
	v_add_f32_e32 v74, 1.0, v74
	v_rcp_f32_e32 v74, v74
	s_nop 0
	v_mul_f32_e32 v73, v73, v74
	v_mul_f32_e32 v74, v72, v73
	v_pk_mul_f32 v[72:73], v[78:79], v[80:81] op_sel_hi:[1,0]
	s_nop 0
	v_mul_f32_e32 v75, 0xbfb8aa3b, v73
	v_exp_f32_e32 v75, v75
	s_nop 0
	v_add_f32_e32 v75, 1.0, v75
	v_rcp_f32_e32 v75, v75
	s_nop 0
	v_mul_f32_e32 v73, v73, v75
; DI unsigned cvt_pk(float lo, float hi) { unsigned r; asm("v_cvt_pk_bf16_f32 %0, %1, %2" : "=v"(r) : "v"(lo), "v"(hi)); return r; }
; DI float siluf_(float x) { return x * sigmoidf_(x); }
;     __device__ __forceinline__ void operator()(const f32x4 (&acc)[2][2][4][2], const Unit& u, int wr, int wc, int fr, int fq) const {
;     ...
;                 const int row = row0 + ai * HALF + m * 16;
;                 const float rs = rsqrtf(ss[row] * (1.f / DM) + EPS);
;                 float h[8];
; #pragma unroll
;                 for (int n = 0; n < 2; ++n)
; #pragma unroll
;                     for (int j = 0; j < 4; ++j) { const float gg = acc[ai][0][m][n][j] * rs, uu = acc[ai][1][m][n][j] * rs; h[4 * n + j] = siluf_(gg) * uu; }
;                 u32x4 w; w.x = cvt_pk(h[0], h[1]); w.y = cvt_pk(h[2], h[3]); w.z = cvt_pk(h[4], h[5]); w.w = cvt_pk(h[6], h[7]);
;                 *(u32x4*)(H + (size_t)row * DFF + col0) = w;
	v_mul_f32_e32 v75, v72, v73
	v_mov_b32_e32 v72, v64
	v_mov_b32_e32 v73, v68
	v_pk_mul_f32 v[72:73], v[72:73], v[80:81] op_sel_hi:[1,0]
	v_mov_b32_e32 v68, v65
	v_mul_f32_e32 v64, 0xbfb8aa3b, v73
	v_exp_f32_e32 v64, v64
	s_nop 0
	v_add_f32_e32 v64, 1.0, v64
	v_rcp_f32_e32 v64, v64
	s_nop 0
	v_mul_f32_e32 v64, v73, v64
	v_mul_f32_e32 v72, v72, v64
	v_pk_mul_f32 v[64:65], v[68:69], v[80:81] op_sel_hi:[1,0]
	s_nop 0
	v_mul_f32_e32 v68, 0xbfb8aa3b, v65
	v_exp_f32_e32 v68, v68
	s_nop 0
	v_add_f32_e32 v68, 1.0, v68
	v_rcp_f32_e32 v68, v68
	s_nop 0
	v_mul_f32_e32 v65, v65, v68
	v_mul_f32_e32 v68, v64, v65
	v_mov_b32_e32 v64, v66
	v_mov_b32_e32 v65, v70
	v_pk_mul_f32 v[64:65], v[64:65], v[80:81] op_sel_hi:[1,0]
	v_mov_b32_e32 v70, v67
	v_mul_f32_e32 v66, 0xbfb8aa3b, v65
	v_exp_f32_e32 v66, v66
	s_nop 0
	v_add_f32_e32 v66, 1.0, v66
	v_rcp_f32_e32 v66, v66
	s_nop 0
	v_mul_f32_e32 v65, v65, v66
	v_mul_f32_e32 v69, v64, v65
	v_pk_mul_f32 v[64:65], v[70:71], v[80:81] op_sel_hi:[1,0]
	s_nop 0
	v_mul_f32_e32 v66, 0xbfb8aa3b, v65
	v_exp_f32_e32 v66, v66
	s_nop 0
	v_add_f32_e32 v66, 1.0, v66
	v_rcp_f32_e32 v66, v66
	s_nop 0
	v_mul_f32_e32 v65, v65, v66
	v_mul_f32_e32 v67, v64, v65
	v_cvt_pk_bf16_f32 v66, v72, v68
	v_cvt_pk_bf16_f32 v67, v69, v67
	v_mad_i64_i32 v[68:69], s[22:23], v81, s64, v[116:117]
	v_lshl_add_u64 v[68:69], v[68:69], 0, v[118:119]
	v_cvt_pk_bf16_f32 v64, v82, v76
	v_cvt_pk_bf16_f32 v65, v74, v75
	global_store_dwordx4 v[68:69], v[64:67], off
	s_nop 0
	s_nop 0
	v_add_u32_e32 v65, 0x80, v138
	v_mov_b32_e32 v67, v60
	v_mov_b32_e32 v60, v57
	v_mov_b32_e32 v64, v165
	v_fmamk_f32 v64, v64, 0x3a800000, v217
	v_cmp_gt_f32_e32 vcc, s15, v64
	v_mul_f32_e32 v66, 0x4b800000, v64
	s_nop 0
	v_cndmask_b32_e32 v64, v64, v66, vcc
	v_rsq_f32_e32 v64, v64
	s_nop 0
	v_mul_f32_e32 v66, 0x45800000, v64
	v_cndmask_b32_e32 v64, v64, v66, vcc
	v_mov_b32_e32 v66, v56
	v_pk_mul_f32 v[66:67], v[66:67], v[64:65] op_sel_hi:[1,0]
	s_nop 0
	v_mul_f32_e32 v56, 0xbfb8aa3b, v67
	v_exp_f32_e32 v56, v56
	s_nop 0
	v_add_f32_e32 v56, 1.0, v56
	v_rcp_f32_e32 v56, v56
	s_nop 0
	v_mul_f32_e32 v56, v67, v56
	v_mul_f32_e32 v66, v66, v56
	v_pk_mul_f32 v[56:57], v[60:61], v[64:65] op_sel_hi:[1,0]
	s_nop 0
	v_mul_f32_e32 v60, 0xbfb8aa3b, v57
	v_exp_f32_e32 v60, v60
	s_nop 0
	v_add_f32_e32 v60, 1.0, v60
	v_rcp_f32_e32 v60, v60
	s_nop 0
	v_mul_f32_e32 v57, v57, v60
	v_mul_f32_e32 v60, v56, v57
	v_mov_b32_e32 v56, v58
	v_mov_b32_e32 v57, v62
	v_pk_mul_f32 v[56:57], v[56:57], v[64:65] op_sel_hi:[1,0]
	v_mov_b32_e32 v62, v59
	v_mul_f32_e32 v58, 0xbfb8aa3b, v57
	v_exp_f32_e32 v58, v58
	s_nop 0
	v_add_f32_e32 v58, 1.0, v58
	v_rcp_f32_e32 v58, v58
	s_nop 0
	v_mul_f32_e32 v57, v57, v58
	v_mul_f32_e32 v58, v56, v57
	v_pk_mul_f32 v[56:57], v[62:63], v[64:65] op_sel_hi:[1,0]
	s_nop 0
	v_mul_f32_e32 v59, 0xbfb8aa3b, v57
	v_exp_f32_e32 v59, v59
	s_nop 0
	v_add_f32_e32 v59, 1.0, v59
	v_rcp_f32_e32 v59, v59
	s_nop 0
	v_mul_f32_e32 v57, v57, v59
	v_mul_f32_e32 v59, v56, v57
	v_mov_b32_e32 v56, v48
	v_mov_b32_e32 v57, v52
	v_pk_mul_f32 v[56:57], v[56:57], v[64:65] op_sel_hi:[1,0]
	v_mov_b32_e32 v52, v49
	v_mul_f32_e32 v48, 0xbfb8aa3b, v57
	v_exp_f32_e32 v48, v48
	s_nop 0
	v_add_f32_e32 v48, 1.0, v48
	v_rcp_f32_e32 v48, v48
	s_nop 0
	v_mul_f32_e32 v48, v57, v48
	v_mul_f32_e32 v56, v56, v48
	v_pk_mul_f32 v[48:49], v[52:53], v[64:65] op_sel_hi:[1,0]
	s_nop 0
	v_mul_f32_e32 v52, 0xbfb8aa3b, v49
	v_exp_f32_e32 v52, v52
	s_nop 0
	v_add_f32_e32 v52, 1.0, v52
	v_rcp_f32_e32 v52, v52
	s_nop 0
	v_mul_f32_e32 v49, v49, v52
	v_mul_f32_e32 v52, v48, v49
	v_mov_b32_e32 v48, v50
	v_mov_b32_e32 v49, v54
	v_pk_mul_f32 v[48:49], v[48:49], v[64:65] op_sel_hi:[1,0]
	v_mov_b32_e32 v54, v51
	v_mul_f32_e32 v50, 0xbfb8aa3b, v49
	v_exp_f32_e32 v50, v50
	s_nop 0
	v_add_f32_e32 v50, 1.0, v50
	v_rcp_f32_e32 v50, v50
	s_nop 0
	v_mul_f32_e32 v49, v49, v50
	v_mul_f32_e32 v53, v48, v49
	v_pk_mul_f32 v[48:49], v[54:55], v[64:65] op_sel_hi:[1,0]
	s_nop 0
	v_mul_f32_e32 v50, 0xbfb8aa3b, v49
	v_exp_f32_e32 v50, v50
	s_nop 0
	v_add_f32_e32 v50, 1.0, v50
	v_rcp_f32_e32 v50, v50
	s_nop 0
	v_mul_f32_e32 v49, v49, v50
	v_mul_f32_e32 v51, v48, v49
	v_cvt_pk_bf16_f32 v50, v56, v52
	v_cvt_pk_bf16_f32 v51, v53, v51
	v_mad_i64_i32 v[52:53], s[22:23], v65, s64, v[116:117]
	v_lshl_add_u64 v[52:53], v[52:53], 0, v[118:119]
	v_cvt_pk_bf16_f32 v48, v66, v60
	v_cvt_pk_bf16_f32 v49, v58, v59
	global_store_dwordx4 v[52:53], v[48:51], off
	s_nop 0
	s_nop 0
	v_add_u32_e32 v49, 0x90, v138
	v_mov_b32_e32 v51, v44
	v_mov_b32_e32 v44, v41
	v_mov_b32_e32 v48, v166
	v_fmamk_f32 v48, v48, 0x3a800000, v217
	v_cmp_gt_f32_e32 vcc, s15, v48
	v_mul_f32_e32 v50, 0x4b800000, v48
	s_nop 0
	v_cndmask_b32_e32 v48, v48, v50, vcc
	v_rsq_f32_e32 v48, v48
	s_nop 0
	v_mul_f32_e32 v50, 0x45800000, v48
	v_cndmask_b32_e32 v48, v48, v50, vcc
	v_mov_b32_e32 v50, v40
	v_pk_mul_f32 v[50:51], v[50:51], v[48:49] op_sel_hi:[1,0]
	s_nop 0
	v_mul_f32_e32 v40, 0xbfb8aa3b, v51
	v_exp_f32_e32 v40, v40
	s_nop 0
	v_add_f32_e32 v40, 1.0, v40
	v_rcp_f32_e32 v40, v40
	s_nop 0
	v_mul_f32_e32 v40, v51, v40
	v_mul_f32_e32 v50, v50, v40
	v_pk_mul_f32 v[40:41], v[44:45], v[48:49] op_sel_hi:[1,0]
	s_nop 0
	v_mul_f32_e32 v44, 0xbfb8aa3b, v41
	v_exp_f32_e32 v44, v44
	s_nop 0
	v_add_f32_e32 v44, 1.0, v44
	v_rcp_f32_e32 v44, v44
	s_nop 0
	v_mul_f32_e32 v41, v41, v44
	v_mul_f32_e32 v44, v40, v41
	v_mov_b32_e32 v40, v42
	v_mov_b32_e32 v41, v46
	v_pk_mul_f32 v[40:41], v[40:41], v[48:49] op_sel_hi:[1,0]
	v_mov_b32_e32 v46, v43
	v_mul_f32_e32 v42, 0xbfb8aa3b, v41
	v_exp_f32_e32 v42, v42
	s_nop 0
	v_add_f32_e32 v42, 1.0, v42
	v_rcp_f32_e32 v42, v42
	s_nop 0
	v_mul_f32_e32 v41, v41, v42
	v_mul_f32_e32 v42, v40, v41
; DI unsigned cvt_pk(float lo, float hi) { unsigned r; asm("v_cvt_pk_bf16_f32 %0, %1, %2" : "=v"(r) : "v"(lo), "v"(hi)); return r; }
; DI float siluf_(float x) { return x * sigmoidf_(x); }
;     __device__ __forceinline__ void operator()(const f32x4 (&acc)[2][2][4][2], const Unit& u, int wr, int wc, int fr, int fq) const {
;     ...
;                 const int row = row0 + ai * HALF + m * 16;
;                 const float rs = rsqrtf(ss[row] * (1.f / DM) + EPS);
;                 float h[8];
; #pragma unroll
;                 for (int n = 0; n < 2; ++n)
; #pragma unroll
;                     for (int j = 0; j < 4; ++j) { const float gg = acc[ai][0][m][n][j] * rs, uu = acc[ai][1][m][n][j] * rs; h[4 * n + j] = siluf_(gg) * uu; }
;                 u32x4 w; w.x = cvt_pk(h[0], h[1]); w.y = cvt_pk(h[2], h[3]); w.z = cvt_pk(h[4], h[5]); w.w = cvt_pk(h[6], h[7]);
;                 *(u32x4*)(H + (size_t)row * DFF + col0) = w;
	v_pk_mul_f32 v[40:41], v[46:47], v[48:49] op_sel_hi:[1,0]
	s_nop 0
	v_mul_f32_e32 v43, 0xbfb8aa3b, v41
	v_exp_f32_e32 v43, v43
	s_nop 0
	v_add_f32_e32 v43, 1.0, v43
	v_rcp_f32_e32 v43, v43
	s_nop 0
	v_mul_f32_e32 v41, v41, v43
	v_mul_f32_e32 v43, v40, v41
	v_mov_b32_e32 v40, v32
	v_mov_b32_e32 v41, v36
	v_pk_mul_f32 v[40:41], v[40:41], v[48:49] op_sel_hi:[1,0]
	v_mov_b32_e32 v36, v33
	v_mul_f32_e32 v32, 0xbfb8aa3b, v41
	v_exp_f32_e32 v32, v32
	s_nop 0
	v_add_f32_e32 v32, 1.0, v32
	v_rcp_f32_e32 v32, v32
	s_nop 0
	v_mul_f32_e32 v32, v41, v32
	v_mul_f32_e32 v40, v40, v32
	v_pk_mul_f32 v[32:33], v[36:37], v[48:49] op_sel_hi:[1,0]
	s_nop 0
	v_mul_f32_e32 v36, 0xbfb8aa3b, v33
	v_exp_f32_e32 v36, v36
	s_nop 0
	v_add_f32_e32 v36, 1.0, v36
	v_rcp_f32_e32 v36, v36
	s_nop 0
	v_mul_f32_e32 v33, v33, v36
	v_mul_f32_e32 v36, v32, v33
	v_mov_b32_e32 v32, v34
	v_mov_b32_e32 v33, v38
	v_pk_mul_f32 v[32:33], v[32:33], v[48:49] op_sel_hi:[1,0]
	v_mov_b32_e32 v38, v35
	v_mul_f32_e32 v34, 0xbfb8aa3b, v33
	v_exp_f32_e32 v34, v34
	s_nop 0
	v_add_f32_e32 v34, 1.0, v34
	v_rcp_f32_e32 v34, v34
	s_nop 0
	v_mul_f32_e32 v33, v33, v34
	v_mul_f32_e32 v37, v32, v33
	v_pk_mul_f32 v[32:33], v[38:39], v[48:49] op_sel_hi:[1,0]
	s_nop 0
	v_mul_f32_e32 v34, 0xbfb8aa3b, v33
	v_exp_f32_e32 v34, v34
	s_nop 0
	v_add_f32_e32 v34, 1.0, v34
	v_rcp_f32_e32 v34, v34
	s_nop 0
	v_mul_f32_e32 v33, v33, v34
	v_mul_f32_e32 v35, v32, v33
	v_cvt_pk_bf16_f32 v34, v40, v36
	v_cvt_pk_bf16_f32 v35, v37, v35
	v_mad_i64_i32 v[36:37], s[22:23], v49, s64, v[116:117]
	v_lshl_add_u64 v[36:37], v[36:37], 0, v[118:119]
	v_cvt_pk_bf16_f32 v32, v50, v44
	v_cvt_pk_bf16_f32 v33, v42, v43
	global_store_dwordx4 v[36:37], v[32:35], off
	s_nop 0
	s_nop 0
	v_add_u32_e32 v33, 0xa0, v138
	v_mov_b32_e32 v35, v28
	v_mov_b32_e32 v28, v25
	v_mov_b32_e32 v32, v167
	v_fmamk_f32 v32, v32, 0x3a800000, v217
	v_cmp_gt_f32_e32 vcc, s15, v32
	v_mul_f32_e32 v34, 0x4b800000, v32
	s_nop 0
	v_cndmask_b32_e32 v32, v32, v34, vcc
	v_rsq_f32_e32 v32, v32
	s_nop 0
	v_mul_f32_e32 v34, 0x45800000, v32
	v_cndmask_b32_e32 v32, v32, v34, vcc
	v_mov_b32_e32 v34, v24
	v_pk_mul_f32 v[34:35], v[34:35], v[32:33] op_sel_hi:[1,0]
	s_nop 0
	v_mul_f32_e32 v24, 0xbfb8aa3b, v35
	v_exp_f32_e32 v24, v24
	s_nop 0
	v_add_f32_e32 v24, 1.0, v24
	v_rcp_f32_e32 v24, v24
	s_nop 0
	v_mul_f32_e32 v24, v35, v24
	v_mul_f32_e32 v34, v34, v24
	v_pk_mul_f32 v[24:25], v[28:29], v[32:33] op_sel_hi:[1,0]
	s_nop 0
	v_mul_f32_e32 v28, 0xbfb8aa3b, v25
	v_exp_f32_e32 v28, v28
	s_nop 0
	v_add_f32_e32 v28, 1.0, v28
	v_rcp_f32_e32 v28, v28
	s_nop 0
	v_mul_f32_e32 v25, v25, v28
	v_mul_f32_e32 v28, v24, v25
	v_mov_b32_e32 v24, v26
	v_mov_b32_e32 v25, v30
	v_pk_mul_f32 v[24:25], v[24:25], v[32:33] op_sel_hi:[1,0]
	v_mov_b32_e32 v30, v27
	v_mul_f32_e32 v26, 0xbfb8aa3b, v25
	v_exp_f32_e32 v26, v26
	s_nop 0
	v_add_f32_e32 v26, 1.0, v26
	v_rcp_f32_e32 v26, v26
	s_nop 0
	v_mul_f32_e32 v25, v25, v26
	v_mul_f32_e32 v26, v24, v25
	v_pk_mul_f32 v[24:25], v[30:31], v[32:33] op_sel_hi:[1,0]
	s_nop 0
	v_mul_f32_e32 v27, 0xbfb8aa3b, v25
	v_exp_f32_e32 v27, v27
	s_nop 0
	v_add_f32_e32 v27, 1.0, v27
	v_rcp_f32_e32 v27, v27
	s_nop 0
	v_mul_f32_e32 v25, v25, v27
	v_mul_f32_e32 v27, v24, v25
	v_mov_b32_e32 v24, v16
	v_mov_b32_e32 v25, v20
	v_pk_mul_f32 v[24:25], v[24:25], v[32:33] op_sel_hi:[1,0]
	v_mov_b32_e32 v20, v17
	v_mul_f32_e32 v16, 0xbfb8aa3b, v25
	v_exp_f32_e32 v16, v16
	s_nop 0
	v_add_f32_e32 v16, 1.0, v16
	v_rcp_f32_e32 v16, v16
	s_nop 0
	v_mul_f32_e32 v16, v25, v16
	v_mul_f32_e32 v24, v24, v16
	v_pk_mul_f32 v[16:17], v[20:21], v[32:33] op_sel_hi:[1,0]
	s_nop 0
	v_mul_f32_e32 v20, 0xbfb8aa3b, v17
	v_exp_f32_e32 v20, v20
	s_nop 0
	v_add_f32_e32 v20, 1.0, v20
	v_rcp_f32_e32 v20, v20
	s_nop 0
	v_mul_f32_e32 v17, v17, v20
	v_mul_f32_e32 v20, v16, v17
	v_mov_b32_e32 v16, v18
; DI unsigned cvt_pk(float lo, float hi) { unsigned r; asm("v_cvt_pk_bf16_f32 %0, %1, %2" : "=v"(r) : "v"(lo), "v"(hi)); return r; }
; DI float siluf_(float x) { return x * sigmoidf_(x); }
; #define PG8_BAR __builtin_amdgcn_s_barrier()
; template <class Epi, class Sched, bool ALIGN_EPI = false, bool SP2 = false>
; __device__ __forceinline__ void gemm_phase(PG8_LAS unsigned char* lds, const Gemm g, const Sched& S, const Epi& E) {
;     ...
;         if constexpr (ALIGN_EPI) { if (wr == 0) PG8_BAR; }
;         E(acc, cur, wr, wc, fr, fq); S.done(cur);
;         if (!has_next) break;
; #pragma unroll
;         for (int a = 0; a < 2; ++a)
; #pragma unroll
;             for (int b = 0; b < 2; ++b)
; #pragma unroll
;                 for (int m = 0; m < 4; ++m)
; #pragma unroll
;                     for (int n = 0; n < 2; ++n) acc[a][b][m][n] = (f32x4){0.f, 0.f, 0.f, 0.f};
;         cur = nxt; cA = nA; cB = nB; ++ui;
;         if constexpr (ALIGN_EPI) { if (wr == 1) PG8_BAR; }
;     __device__ __forceinline__ void operator()(const f32x4 (&acc)[2][2][4][2], const Unit& u, int wr, int wc, int fr, int fq) const {
;     ...
;                 const int row = row0 + ai * HALF + m * 16;
;                 const float rs = rsqrtf(ss[row] * (1.f / DM) + EPS);
;                 float h[8];
; #pragma unroll
;                 for (int n = 0; n < 2; ++n)
; #pragma unroll
;                     for (int j = 0; j < 4; ++j) { const float gg = acc[ai][0][m][n][j] * rs, uu = acc[ai][1][m][n][j] * rs; h[4 * n + j] = siluf_(gg) * uu; }
;                 u32x4 w; w.x = cvt_pk(h[0], h[1]); w.y = cvt_pk(h[2], h[3]); w.z = cvt_pk(h[4], h[5]); w.w = cvt_pk(h[6], h[7]);
;                 *(u32x4*)(H + (size_t)row * DFF + col0) = w;
	v_mov_b32_e32 v17, v22
	v_pk_mul_f32 v[16:17], v[16:17], v[32:33] op_sel_hi:[1,0]
	v_mov_b32_e32 v22, v19
	v_mul_f32_e32 v18, 0xbfb8aa3b, v17
	v_exp_f32_e32 v18, v18
	s_nop 0
	v_add_f32_e32 v18, 1.0, v18
	v_rcp_f32_e32 v18, v18
	s_nop 0
	v_mul_f32_e32 v17, v17, v18
	v_mul_f32_e32 v21, v16, v17
	v_pk_mul_f32 v[16:17], v[22:23], v[32:33] op_sel_hi:[1,0]
	s_nop 0
	v_mul_f32_e32 v18, 0xbfb8aa3b, v17
	v_exp_f32_e32 v18, v18
	s_nop 0
	v_add_f32_e32 v18, 1.0, v18
	v_rcp_f32_e32 v18, v18
	s_nop 0
	v_mul_f32_e32 v17, v17, v18
	v_mul_f32_e32 v19, v16, v17
	v_cvt_pk_bf16_f32 v18, v24, v20
	v_cvt_pk_bf16_f32 v19, v21, v19
	v_mad_i64_i32 v[20:21], s[22:23], v33, s64, v[116:117]
	v_lshl_add_u64 v[20:21], v[20:21], 0, v[118:119]
	v_cvt_pk_bf16_f32 v16, v34, v28
	v_cvt_pk_bf16_f32 v17, v26, v27
	global_store_dwordx4 v[20:21], v[16:19], off
	s_nop 0
	s_nop 0
	v_add_u32_e32 v17, 0xb0, v138
	v_mov_b32_e32 v19, v12
	v_mov_b32_e32 v12, v9
	v_mov_b32_e32 v16, v168
	v_fmamk_f32 v16, v16, 0x3a800000, v217
	v_cmp_gt_f32_e32 vcc, s15, v16
	v_mul_f32_e32 v18, 0x4b800000, v16
	s_nop 0
	v_cndmask_b32_e32 v16, v16, v18, vcc
	v_rsq_f32_e32 v16, v16
	s_nop 0
	v_mul_f32_e32 v18, 0x45800000, v16
	v_cndmask_b32_e32 v16, v16, v18, vcc
	v_mov_b32_e32 v18, v8
	v_pk_mul_f32 v[18:19], v[18:19], v[16:17] op_sel_hi:[1,0]
	s_andn2_b64 vcc, exec, s[6:7]
	v_mul_f32_e32 v8, 0xbfb8aa3b, v19
	v_exp_f32_e32 v8, v8
	s_nop 0
	v_add_f32_e32 v8, 1.0, v8
	v_rcp_f32_e32 v8, v8
	s_nop 0
	v_mul_f32_e32 v8, v19, v8
	v_mul_f32_e32 v18, v18, v8
	v_pk_mul_f32 v[8:9], v[12:13], v[16:17] op_sel_hi:[1,0]
	s_nop 0
	v_mul_f32_e32 v12, 0xbfb8aa3b, v9
	v_exp_f32_e32 v12, v12
	s_nop 0
	v_add_f32_e32 v12, 1.0, v12
	v_rcp_f32_e32 v12, v12
	s_nop 0
	v_mul_f32_e32 v9, v9, v12
	v_mul_f32_e32 v12, v8, v9
	v_mov_b32_e32 v8, v10
	v_mov_b32_e32 v9, v14
	v_pk_mul_f32 v[8:9], v[8:9], v[16:17] op_sel_hi:[1,0]
	v_mov_b32_e32 v14, v11
	v_mul_f32_e32 v10, 0xbfb8aa3b, v9
	v_exp_f32_e32 v10, v10
	s_nop 0
	v_add_f32_e32 v10, 1.0, v10
	v_rcp_f32_e32 v10, v10
	s_nop 0
	v_mul_f32_e32 v9, v9, v10
	v_mul_f32_e32 v10, v8, v9
	v_pk_mul_f32 v[8:9], v[14:15], v[16:17] op_sel_hi:[1,0]
	s_nop 0
	v_mul_f32_e32 v11, 0xbfb8aa3b, v9
	v_exp_f32_e32 v11, v11
	s_nop 0
	v_add_f32_e32 v11, 1.0, v11
	v_rcp_f32_e32 v11, v11
	s_nop 0
	v_mul_f32_e32 v9, v9, v11
	v_mul_f32_e32 v11, v8, v9
	v_mov_b32_e32 v8, v0
	v_mov_b32_e32 v9, v4
	v_pk_mul_f32 v[8:9], v[8:9], v[16:17] op_sel_hi:[1,0]
	v_mov_b32_e32 v4, v1
	v_mul_f32_e32 v0, 0xbfb8aa3b, v9
	v_exp_f32_e32 v0, v0
	s_nop 0
	v_add_f32_e32 v0, 1.0, v0
	v_rcp_f32_e32 v0, v0
	s_nop 0
	v_mul_f32_e32 v0, v9, v0
	v_mul_f32_e32 v8, v8, v0
	v_pk_mul_f32 v[0:1], v[4:5], v[16:17] op_sel_hi:[1,0]
	s_nop 0
	v_mul_f32_e32 v4, 0xbfb8aa3b, v1
	v_exp_f32_e32 v4, v4
	s_nop 0
	v_add_f32_e32 v4, 1.0, v4
	v_rcp_f32_e32 v4, v4
	s_nop 0
	v_mul_f32_e32 v1, v1, v4
	v_mul_f32_e32 v4, v0, v1
	v_mov_b32_e32 v0, v2
	v_mov_b32_e32 v1, v6
	v_pk_mul_f32 v[0:1], v[0:1], v[16:17] op_sel_hi:[1,0]
	v_mov_b32_e32 v6, v3
	v_mul_f32_e32 v2, 0xbfb8aa3b, v1
	v_exp_f32_e32 v2, v2
	s_nop 0
	v_add_f32_e32 v2, 1.0, v2
	v_rcp_f32_e32 v2, v2
	s_nop 0
	v_mul_f32_e32 v1, v1, v2
	v_mul_f32_e32 v5, v0, v1
	v_pk_mul_f32 v[0:1], v[6:7], v[16:17] op_sel_hi:[1,0]
	s_nop 0
	v_mul_f32_e32 v2, 0xbfb8aa3b, v1
	v_exp_f32_e32 v2, v2
	s_nop 0
	v_add_f32_e32 v2, 1.0, v2
	v_rcp_f32_e32 v2, v2
	s_nop 0
	v_mul_f32_e32 v1, v1, v2
	v_mul_f32_e32 v3, v0, v1
	v_cvt_pk_bf16_f32 v2, v8, v4
	v_cvt_pk_bf16_f32 v3, v5, v3
	v_mad_i64_i32 v[4:5], s[22:23], v17, s64, v[116:117]
	v_lshl_add_u64 v[4:5], v[4:5], 0, v[118:119]
	s_mov_b64 s[22:23], -1
	v_cvt_pk_bf16_f32 v0, v18, v12
	v_cvt_pk_bf16_f32 v1, v10, v11
	global_store_dwordx4 v[4:5], v[0:3], off
	s_cbranch_vccnz .LBB0_1287
	s_andn2_b64 vcc, exec, s[2:3]
	s_cbranch_vccnz .LBB0_1286
	s_barrier
	s_branch .LBB0_1286
